# expert gather in ascending expert-id order per token (in-register bitonic sort) for XCD L2 locality
# speedup vs baseline: 1.0118x; 1.0118x over previous
; __device__ __forceinline__ void phase_expert(CArgs& A, int l, unsigned char* lds, int tid, bool dry = false) {
;     ...
;         const int id0 = IDX[(size_t)t * 128 + lane], id1 = IDX[(size_t)t * 128 + 64 + lane];
;         const float gl0 = GATE[(size_t)t * 128 + lane], gl1 = GATE[(size_t)t * 128 + 64 + lane];
;         float xinv; int xh0 = 0, xh1 = 0, xl0 = 0, xl1 = 0;
;         { float am = 0.f;
; #pragma unroll
;           for (int i = 0; i < 8; ++i) am = fmaxf(am, fmaxf(fabsf(x[i].x), fabsf(x[i].y)));
; #pragma unroll
;           for (int o = 1; o < 64; o <<= 1) am = fmaxf(am, __shfl_xor(am, o));
;           const float xs = 119.f / fmaxf(am, 1e-20f); xinv = 1.f / (xs * U_SCALE);
; #pragma unroll
;           for (int i = 0; i < 16; ++i) { const float xv = (i & 1) ? x[i >> 1].y : x[i >> 1].x; const int q = (int)rintf(xv * xs);
;               const int lo = ((q + 8) & 15) - 8, hi = (q - lo) >> 4;
;               if (i < 8) { xl0 |= (lo & 15) << (4 * i); xh0 |= (hi & 15) << (4 * i); } else { xl1 |= (lo & 15) << (4 * (i - 8)); xh1 |= (hi & 15) << (4 * (i - 8)); } } }
;         u32x2 ur[2][8], vr[2][8]; float gtv[2];
.LBB0_41:
	v_ashrrev_i32_e32 v127, 31, v126
	v_lshlrev_b64 v[34:35], 11, v[126:127]
	v_lshl_add_u64 v[138:139], v[130:131], 0, v[34:35]
	v_lshlrev_b32_e32 v1, 9, v126
	v_lshl_or_b32 v1, v128, 2, v1
	global_load_dword v210, v1, s[6:7]
	global_load_dword v211, v1, s[6:7] offset:256
	global_load_dword v212, v1, s[56:57]
	global_load_dword v213, v1, s[56:57] offset:256
	global_load_dwordx2 v[34:35], v[138:139], off
	global_load_dwordx2 v[36:37], v[138:139], off offset:512
	global_load_dwordx2 v[38:39], v[138:139], off offset:1024
	global_load_dwordx2 v[40:41], v[138:139], off offset:1536
	s_mov_b32 s0, 0x1e3ce508
	s_mov_b32 s4, 0x42ee0000
	v_mov_b32_e32 v158, 0
	v_lshlrev_b64 v[136:137], 10, v[126:127]
	s_mov_b32 s8, 0
	v_mov_b32_e32 v159, v158
	v_mov_b32_e32 v160, v158
	v_mov_b32_e32 v161, v158
	s_waitcnt vmcnt(0)
	v_readlane_b32 s11, v210, 0
	s_lshl_b32 s11, s11, 10
	s_add_u32 s48, s72, s11
	s_addc_u32 s49, s73, 0
	global_load_dwordx4 v[80:83], v219, s[48:49]
	v_readlane_b32 s37, v210, 1
	s_lshl_b32 s37, s37, 10
	s_add_u32 s50, s72, s37
	s_addc_u32 s51, s73, 0
	global_load_dwordx4 v[84:87], v219, s[50:51]
	v_readlane_b32 s11, v210, 2
	s_lshl_b32 s11, s11, 10
	s_add_u32 s48, s72, s11
	s_addc_u32 s49, s73, 0
	global_load_dwordx4 v[88:91], v219, s[48:49]
	v_readlane_b32 s37, v210, 3
	s_lshl_b32 s37, s37, 10
	s_add_u32 s50, s72, s37
	s_addc_u32 s51, s73, 0
	global_load_dwordx4 v[92:95], v219, s[50:51]
	v_readlane_b32 s11, v210, 4
	s_lshl_b32 s11, s11, 10
	s_add_u32 s48, s72, s11
	s_addc_u32 s49, s73, 0
	global_load_dwordx4 v[96:99], v219, s[48:49]
	v_readlane_b32 s37, v210, 5
	s_lshl_b32 s37, s37, 10
	s_add_u32 s50, s72, s37
	s_addc_u32 s51, s73, 0
	global_load_dwordx4 v[100:103], v219, s[50:51]
	v_readlane_b32 s11, v210, 6
	s_lshl_b32 s11, s11, 10
	s_add_u32 s48, s72, s11
	s_addc_u32 s49, s73, 0
	global_load_dwordx4 v[104:107], v219, s[48:49]
	v_readlane_b32 s37, v210, 7
	s_lshl_b32 s37, s37, 10
	s_add_u32 s50, s72, s37
	s_addc_u32 s51, s73, 0
	global_load_dwordx4 v[108:111], v219, s[50:51]
	v_readlane_b32 s11, v210, 8
	s_lshl_b32 s11, s11, 10
	s_add_u32 s48, s72, s11
	s_addc_u32 s49, s73, 0
	global_load_dwordx4 v[112:115], v219, s[48:49]
	v_readlane_b32 s37, v210, 9
	s_lshl_b32 s37, s37, 10
	s_add_u32 s50, s72, s37
	s_addc_u32 s51, s73, 0
	global_load_dwordx4 v[116:119], v219, s[50:51]
	v_readlane_b32 s11, v210, 10
	s_lshl_b32 s11, s11, 10
	s_add_u32 s48, s72, s11
	s_addc_u32 s49, s73, 0
	global_load_dwordx4 v[120:123], v219, s[48:49]
	v_readlane_b32 s37, v210, 11
	s_lshl_b32 s37, s37, 10
	s_add_u32 s50, s72, s37
	s_addc_u32 s51, s73, 0
	global_load_dwordx4 v[220:223], v219, s[50:51]
	v_readlane_b32 s11, v210, 12
	s_lshl_b32 s11, s11, 10
	s_add_u32 s48, s72, s11
	s_addc_u32 s49, s73, 0
	global_load_dwordx4 v[224:227], v219, s[48:49]
	v_readlane_b32 s37, v210, 13
	s_lshl_b32 s37, s37, 10
	s_add_u32 s50, s72, s37
	s_addc_u32 s51, s73, 0
	global_load_dwordx4 v[228:231], v219, s[50:51]
	v_readlane_b32 s11, v210, 14
	s_lshl_b32 s11, s11, 10
	s_add_u32 s48, s72, s11
	s_addc_u32 s49, s73, 0
	global_load_dwordx4 v[232:235], v219, s[48:49]
	v_readlane_b32 s37, v210, 15
	s_lshl_b32 s37, s37, 10
	s_add_u32 s50, s72, s37
	s_addc_u32 s51, s73, 0
	global_load_dwordx4 v[236:239], v219, s[50:51]
	v_lshl_or_b32 v129, v210, 7, v128
	v_or_b32_e32 v42, 64, v128
	v_or_b32_e32 v43, 0xffffff80, v128
	v_cmp_gt_u32_e32 vcc, 24, v128
	v_lshl_or_b32 v132, v211, 7, v42
	s_nop 0
	v_cndmask_b32_e32 v129, v129, v43, vcc
	s_mov_b32 s74, 0x99999999
	s_mov_b32 s75, 0x99999999
	s_nop 1
	v_mov_b32_dpp v42, v129 quad_perm:[1,0,3,2] row_mask:0xf bank_mask:0xf
	v_mov_b32_dpp v43, v132 quad_perm:[1,0,3,2] row_mask:0xf bank_mask:0xf
	v_min_u32_e32 v44, v129, v42
	v_max_u32_e32 v45, v129, v42
	v_cndmask_b32_e64 v129, v45, v44, s[74:75]
	v_min_u32_e32 v44, v132, v43
	v_max_u32_e32 v45, v132, v43
	v_cndmask_b32_e64 v132, v45, v44, s[74:75]
	s_mov_b32 s74, 0xc3c3c3c3
	s_mov_b32 s75, 0xc3c3c3c3
	s_nop 1
	v_mov_b32_dpp v42, v129 quad_perm:[2,3,0,1] row_mask:0xf bank_mask:0xf
	v_mov_b32_dpp v43, v132 quad_perm:[2,3,0,1] row_mask:0xf bank_mask:0xf
	v_min_u32_e32 v44, v129, v42
	v_max_u32_e32 v45, v129, v42
	v_cndmask_b32_e64 v129, v45, v44, s[74:75]
	v_min_u32_e32 v44, v132, v43
	v_max_u32_e32 v45, v132, v43
	v_cndmask_b32_e64 v132, v45, v44, s[74:75]
	s_mov_b32 s74, 0xa5a5a5a5
	s_mov_b32 s75, 0xa5a5a5a5
	s_nop 1
	v_mov_b32_dpp v42, v129 quad_perm:[1,0,3,2] row_mask:0xf bank_mask:0xf
	v_mov_b32_dpp v43, v132 quad_perm:[1,0,3,2] row_mask:0xf bank_mask:0xf
	v_min_u32_e32 v44, v129, v42
	v_max_u32_e32 v45, v129, v42
	v_cndmask_b32_e64 v129, v45, v44, s[74:75]
	v_min_u32_e32 v44, v132, v43
	v_max_u32_e32 v45, v132, v43
	v_cndmask_b32_e64 v132, v45, v44, s[74:75]
	s_mov_b32 s74, 0xf00ff00f
	s_mov_b32 s75, 0xf00ff00f
	s_nop 1
	v_mov_b32_dpp v42, v129 row_shl:4 row_mask:0xf bank_mask:0x5
	s_nop 1
	v_mov_b32_dpp v42, v129 row_shr:4 row_mask:0xf bank_mask:0xa
	v_mov_b32_dpp v43, v132 row_shl:4 row_mask:0xf bank_mask:0x5
	s_nop 1
	v_mov_b32_dpp v43, v132 row_shr:4 row_mask:0xf bank_mask:0xa
	s_nop 0
	v_min_u32_e32 v44, v129, v42
	v_max_u32_e32 v45, v129, v42
	v_cndmask_b32_e64 v129, v45, v44, s[74:75]
	v_min_u32_e32 v44, v132, v43
	v_max_u32_e32 v45, v132, v43
	v_cndmask_b32_e64 v132, v45, v44, s[74:75]
	s_mov_b32 s74, 0xcc33cc33
	s_mov_b32 s75, 0xcc33cc33
	s_nop 1
	v_mov_b32_dpp v42, v129 quad_perm:[2,3,0,1] row_mask:0xf bank_mask:0xf
	v_mov_b32_dpp v43, v132 quad_perm:[2,3,0,1] row_mask:0xf bank_mask:0xf
	v_min_u32_e32 v44, v129, v42
	v_max_u32_e32 v45, v129, v42
	v_cndmask_b32_e64 v129, v45, v44, s[74:75]
	v_min_u32_e32 v44, v132, v43
	v_max_u32_e32 v45, v132, v43
	v_cndmask_b32_e64 v132, v45, v44, s[74:75]
	s_mov_b32 s74, 0xaa55aa55
	s_mov_b32 s75, 0xaa55aa55
	s_nop 1
	v_mov_b32_dpp v42, v129 quad_perm:[1,0,3,2] row_mask:0xf bank_mask:0xf
	v_mov_b32_dpp v43, v132 quad_perm:[1,0,3,2] row_mask:0xf bank_mask:0xf
	v_min_u32_e32 v44, v129, v42
	v_max_u32_e32 v45, v129, v42
	v_cndmask_b32_e64 v129, v45, v44, s[74:75]
	v_min_u32_e32 v44, v132, v43
	v_max_u32_e32 v45, v132, v43
	v_cndmask_b32_e64 v132, v45, v44, s[74:75]
	s_mov_b32 s74, 0xff0000ff
	s_mov_b32 s75, 0xff0000ff
	s_nop 1
	v_mov_b32_dpp v42, v129 row_ror:8 row_mask:0xf bank_mask:0xf
	v_mov_b32_dpp v43, v132 row_ror:8 row_mask:0xf bank_mask:0xf
	v_min_u32_e32 v44, v129, v42
	v_max_u32_e32 v45, v129, v42
	v_cndmask_b32_e64 v129, v45, v44, s[74:75]
	v_min_u32_e32 v44, v132, v43
	v_max_u32_e32 v45, v132, v43
	v_cndmask_b32_e64 v132, v45, v44, s[74:75]
	s_mov_b32 s74, 0xf0f00f0f
	s_mov_b32 s75, 0xf0f00f0f
	s_nop 1
	v_mov_b32_dpp v42, v129 row_shl:4 row_mask:0xf bank_mask:0x5
	s_nop 1
	v_mov_b32_dpp v42, v129 row_shr:4 row_mask:0xf bank_mask:0xa
	v_mov_b32_dpp v43, v132 row_shl:4 row_mask:0xf bank_mask:0x5
	s_nop 1
	v_mov_b32_dpp v43, v132 row_shr:4 row_mask:0xf bank_mask:0xa
	s_nop 0
	v_min_u32_e32 v44, v129, v42
	v_max_u32_e32 v45, v129, v42
	v_cndmask_b32_e64 v129, v45, v44, s[74:75]
	v_min_u32_e32 v44, v132, v43
	v_max_u32_e32 v45, v132, v43
	v_cndmask_b32_e64 v132, v45, v44, s[74:75]
	s_mov_b32 s74, 0xcccc3333
	s_mov_b32 s75, 0xcccc3333
	s_nop 1
	v_mov_b32_dpp v42, v129 quad_perm:[2,3,0,1] row_mask:0xf bank_mask:0xf
	v_mov_b32_dpp v43, v132 quad_perm:[2,3,0,1] row_mask:0xf bank_mask:0xf
	v_min_u32_e32 v44, v129, v42
	v_max_u32_e32 v45, v129, v42
	v_cndmask_b32_e64 v129, v45, v44, s[74:75]
	v_min_u32_e32 v44, v132, v43
	v_max_u32_e32 v45, v132, v43
	v_cndmask_b32_e64 v132, v45, v44, s[74:75]
	s_mov_b32 s74, 0xaaaa5555
	s_mov_b32 s75, 0xaaaa5555
	s_nop 1
	v_mov_b32_dpp v42, v129 quad_perm:[1,0,3,2] row_mask:0xf bank_mask:0xf
	v_mov_b32_dpp v43, v132 quad_perm:[1,0,3,2] row_mask:0xf bank_mask:0xf
	v_min_u32_e32 v44, v129, v42
	v_max_u32_e32 v45, v129, v42
	v_cndmask_b32_e64 v129, v45, v44, s[74:75]
	v_min_u32_e32 v44, v132, v43
	v_max_u32_e32 v45, v132, v43
	v_cndmask_b32_e64 v132, v45, v44, s[74:75]
	s_mov_b32 s74, 0xffff
	s_mov_b32 s75, 0xffff0000
	ds_bpermute_b32 v42, v195, v129
	ds_bpermute_b32 v43, v195, v132
	s_waitcnt lgkmcnt(0)
	v_min_u32_e32 v44, v129, v42
	v_max_u32_e32 v45, v129, v42
	v_cndmask_b32_e64 v129, v45, v44, s[74:75]
	v_min_u32_e32 v44, v132, v43
	v_max_u32_e32 v45, v132, v43
	v_cndmask_b32_e64 v132, v45, v44, s[74:75]
	s_mov_b32 s74, 0xff00ff
	s_mov_b32 s75, 0xff00ff00
	s_nop 1
	v_mov_b32_dpp v42, v129 row_ror:8 row_mask:0xf bank_mask:0xf
	v_mov_b32_dpp v43, v132 row_ror:8 row_mask:0xf bank_mask:0xf
	v_min_u32_e32 v44, v129, v42
	v_max_u32_e32 v45, v129, v42
	v_cndmask_b32_e64 v129, v45, v44, s[74:75]
	v_min_u32_e32 v44, v132, v43
	v_max_u32_e32 v45, v132, v43
	v_cndmask_b32_e64 v132, v45, v44, s[74:75]
	s_mov_b32 s74, 0xf0f0f0f
	s_mov_b32 s75, 0xf0f0f0f0
	s_nop 1
	v_mov_b32_dpp v42, v129 row_shl:4 row_mask:0xf bank_mask:0x5
	s_nop 1
	v_mov_b32_dpp v42, v129 row_shr:4 row_mask:0xf bank_mask:0xa
	v_mov_b32_dpp v43, v132 row_shl:4 row_mask:0xf bank_mask:0x5
	s_nop 1
	v_mov_b32_dpp v43, v132 row_shr:4 row_mask:0xf bank_mask:0xa
	s_nop 0
	v_min_u32_e32 v44, v129, v42
	v_max_u32_e32 v45, v129, v42
	v_cndmask_b32_e64 v129, v45, v44, s[74:75]
	v_min_u32_e32 v44, v132, v43
	v_max_u32_e32 v45, v132, v43
	v_cndmask_b32_e64 v132, v45, v44, s[74:75]
	s_mov_b32 s74, 0x33333333
	s_mov_b32 s75, 0xcccccccc
	s_nop 1
	v_mov_b32_dpp v42, v129 quad_perm:[2,3,0,1] row_mask:0xf bank_mask:0xf
	v_mov_b32_dpp v43, v132 quad_perm:[2,3,0,1] row_mask:0xf bank_mask:0xf
	v_min_u32_e32 v44, v129, v42
	v_max_u32_e32 v45, v129, v42
	v_cndmask_b32_e64 v129, v45, v44, s[74:75]
	v_min_u32_e32 v44, v132, v43
	v_max_u32_e32 v45, v132, v43
	v_cndmask_b32_e64 v132, v45, v44, s[74:75]
	s_mov_b32 s74, 0x55555555
	s_mov_b32 s75, 0xaaaaaaaa
	s_nop 1
	v_mov_b32_dpp v42, v129 quad_perm:[1,0,3,2] row_mask:0xf bank_mask:0xf
	v_mov_b32_dpp v43, v132 quad_perm:[1,0,3,2] row_mask:0xf bank_mask:0xf
	v_min_u32_e32 v44, v129, v42
	v_max_u32_e32 v45, v129, v42
	v_cndmask_b32_e64 v129, v45, v44, s[74:75]
	v_min_u32_e32 v44, v132, v43
	v_max_u32_e32 v45, v132, v43
	v_cndmask_b32_e64 v132, v45, v44, s[74:75]
	s_mov_b32 s74, 0xffffffff
	s_mov_b32 s75, 0x0
	s_mov_b32 s48, 0x0
	s_mov_b32 s49, 0xffffffff
	ds_bpermute_b32 v42, v196, v129
	ds_bpermute_b32 v43, v196, v132
	s_waitcnt lgkmcnt(0)
	v_min_u32_e32 v44, v129, v42
	v_max_u32_e32 v45, v129, v42
	v_cndmask_b32_e64 v129, v45, v44, s[74:75]
	v_min_u32_e32 v44, v132, v43
	v_max_u32_e32 v45, v132, v43
	v_cndmask_b32_e64 v132, v45, v44, s[48:49]
	s_mov_b32 s74, 0xffff
	s_mov_b32 s75, 0xffff
	s_mov_b32 s48, 0xffff0000
	s_mov_b32 s49, 0xffff0000
	ds_bpermute_b32 v42, v195, v129
	ds_bpermute_b32 v43, v195, v132
	s_waitcnt lgkmcnt(0)
	v_min_u32_e32 v44, v129, v42
	v_max_u32_e32 v45, v129, v42
	v_cndmask_b32_e64 v129, v45, v44, s[74:75]
	v_min_u32_e32 v44, v132, v43
	v_max_u32_e32 v45, v132, v43
	v_cndmask_b32_e64 v132, v45, v44, s[48:49]
	s_mov_b32 s74, 0xff00ff
	s_mov_b32 s75, 0xff00ff
	s_mov_b32 s48, 0xff00ff00
	s_mov_b32 s49, 0xff00ff00
	s_nop 1
	v_mov_b32_dpp v42, v129 row_ror:8 row_mask:0xf bank_mask:0xf
	v_mov_b32_dpp v43, v132 row_ror:8 row_mask:0xf bank_mask:0xf
	v_min_u32_e32 v44, v129, v42
	v_max_u32_e32 v45, v129, v42
	v_cndmask_b32_e64 v129, v45, v44, s[74:75]
	v_min_u32_e32 v44, v132, v43
	v_max_u32_e32 v45, v132, v43
	v_cndmask_b32_e64 v132, v45, v44, s[48:49]
	s_mov_b32 s74, 0xf0f0f0f
	s_mov_b32 s75, 0xf0f0f0f
	s_mov_b32 s48, 0xf0f0f0f0
	s_mov_b32 s49, 0xf0f0f0f0
	s_nop 1
	v_mov_b32_dpp v42, v129 row_shl:4 row_mask:0xf bank_mask:0x5
	s_nop 1
	v_mov_b32_dpp v42, v129 row_shr:4 row_mask:0xf bank_mask:0xa
	v_mov_b32_dpp v43, v132 row_shl:4 row_mask:0xf bank_mask:0x5
	s_nop 1
	v_mov_b32_dpp v43, v132 row_shr:4 row_mask:0xf bank_mask:0xa
	s_nop 0
	v_min_u32_e32 v44, v129, v42
	v_max_u32_e32 v45, v129, v42
	v_cndmask_b32_e64 v129, v45, v44, s[74:75]
	v_min_u32_e32 v44, v132, v43
	v_max_u32_e32 v45, v132, v43
	v_cndmask_b32_e64 v132, v45, v44, s[48:49]
	s_mov_b32 s74, 0x33333333
	s_mov_b32 s75, 0x33333333
	s_mov_b32 s48, 0xcccccccc
	s_mov_b32 s49, 0xcccccccc
	s_nop 1
	v_mov_b32_dpp v42, v129 quad_perm:[2,3,0,1] row_mask:0xf bank_mask:0xf
	v_mov_b32_dpp v43, v132 quad_perm:[2,3,0,1] row_mask:0xf bank_mask:0xf
	v_min_u32_e32 v44, v129, v42
	v_max_u32_e32 v45, v129, v42
	v_cndmask_b32_e64 v129, v45, v44, s[74:75]
	v_min_u32_e32 v44, v132, v43
	v_max_u32_e32 v45, v132, v43
	v_cndmask_b32_e64 v132, v45, v44, s[48:49]
	s_mov_b32 s74, 0x55555555
	s_mov_b32 s75, 0x55555555
	s_mov_b32 s48, 0xaaaaaaaa
	s_mov_b32 s49, 0xaaaaaaaa
	s_nop 1
	v_mov_b32_dpp v42, v129 quad_perm:[1,0,3,2] row_mask:0xf bank_mask:0xf
	v_mov_b32_dpp v43, v132 quad_perm:[1,0,3,2] row_mask:0xf bank_mask:0xf
	v_min_u32_e32 v44, v129, v42
	v_max_u32_e32 v45, v129, v42
	v_cndmask_b32_e64 v129, v45, v44, s[74:75]
	v_min_u32_e32 v44, v132, v43
	v_max_u32_e32 v45, v132, v43
	v_cndmask_b32_e64 v132, v45, v44, s[48:49]
	v_min_u32_e32 v44, v129, v132
	v_max_u32_e32 v132, v129, v132
	v_mov_b32_e32 v129, v44
	s_mov_b32 s74, 0xffffffff
	s_mov_b32 s75, 0x0
	ds_bpermute_b32 v42, v196, v129
	ds_bpermute_b32 v43, v196, v132
	s_waitcnt lgkmcnt(0)
	v_min_u32_e32 v44, v129, v42
	v_max_u32_e32 v45, v129, v42
	v_cndmask_b32_e64 v129, v45, v44, s[74:75]
	v_min_u32_e32 v44, v132, v43
	v_max_u32_e32 v45, v132, v43
	v_cndmask_b32_e64 v132, v45, v44, s[74:75]
	s_mov_b32 s74, 0xffff
	s_mov_b32 s75, 0xffff
	ds_bpermute_b32 v42, v195, v129
	ds_bpermute_b32 v43, v195, v132
	s_waitcnt lgkmcnt(0)
	v_min_u32_e32 v44, v129, v42
	v_max_u32_e32 v45, v129, v42
	v_cndmask_b32_e64 v129, v45, v44, s[74:75]
	v_min_u32_e32 v44, v132, v43
	v_max_u32_e32 v45, v132, v43
	v_cndmask_b32_e64 v132, v45, v44, s[74:75]
	s_mov_b32 s74, 0xff00ff
	s_mov_b32 s75, 0xff00ff
	s_nop 1
	v_mov_b32_dpp v42, v129 row_ror:8 row_mask:0xf bank_mask:0xf
	v_mov_b32_dpp v43, v132 row_ror:8 row_mask:0xf bank_mask:0xf
	v_min_u32_e32 v44, v129, v42
	v_max_u32_e32 v45, v129, v42
	v_cndmask_b32_e64 v129, v45, v44, s[74:75]
	v_min_u32_e32 v44, v132, v43
	v_max_u32_e32 v45, v132, v43
	v_cndmask_b32_e64 v132, v45, v44, s[74:75]
	s_mov_b32 s74, 0xf0f0f0f
	s_mov_b32 s75, 0xf0f0f0f
	s_nop 1
	v_mov_b32_dpp v42, v129 row_shl:4 row_mask:0xf bank_mask:0x5
	s_nop 1
	v_mov_b32_dpp v42, v129 row_shr:4 row_mask:0xf bank_mask:0xa
	v_mov_b32_dpp v43, v132 row_shl:4 row_mask:0xf bank_mask:0x5
	s_nop 1
	v_mov_b32_dpp v43, v132 row_shr:4 row_mask:0xf bank_mask:0xa
	s_nop 0
	v_min_u32_e32 v44, v129, v42
	v_max_u32_e32 v45, v129, v42
	v_cndmask_b32_e64 v129, v45, v44, s[74:75]
	v_min_u32_e32 v44, v132, v43
	v_max_u32_e32 v45, v132, v43
	v_cndmask_b32_e64 v132, v45, v44, s[74:75]
	s_mov_b32 s74, 0x33333333
	s_mov_b32 s75, 0x33333333
	s_nop 1
	v_mov_b32_dpp v42, v129 quad_perm:[2,3,0,1] row_mask:0xf bank_mask:0xf
	v_mov_b32_dpp v43, v132 quad_perm:[2,3,0,1] row_mask:0xf bank_mask:0xf
	v_min_u32_e32 v44, v129, v42
	v_max_u32_e32 v45, v129, v42
	v_cndmask_b32_e64 v129, v45, v44, s[74:75]
	v_min_u32_e32 v44, v132, v43
	v_max_u32_e32 v45, v132, v43
	v_cndmask_b32_e64 v132, v45, v44, s[74:75]
	s_mov_b32 s74, 0x55555555
	s_mov_b32 s75, 0x55555555
	s_nop 1
	v_mov_b32_dpp v42, v129 quad_perm:[1,0,3,2] row_mask:0xf bank_mask:0xf
	v_mov_b32_dpp v43, v132 quad_perm:[1,0,3,2] row_mask:0xf bank_mask:0xf
	v_min_u32_e32 v44, v129, v42
	v_max_u32_e32 v45, v129, v42
	v_cndmask_b32_e64 v129, v45, v44, s[74:75]
	v_min_u32_e32 v44, v132, v43
	v_max_u32_e32 v45, v132, v43
	v_cndmask_b32_e64 v132, v45, v44, s[74:75]
	v_and_b32_e32 v46, 63, v129
	v_and_b32_e32 v47, 63, v132
	v_lshlrev_b32_e32 v46, 2, v46
	v_lshlrev_b32_e32 v47, 2, v47
	ds_bpermute_b32 v48, v46, v212
	ds_bpermute_b32 v49, v46, v213
	ds_bpermute_b32 v50, v47, v212
	ds_bpermute_b32 v51, v47, v213
	v_and_b32_e32 v46, 64, v129
	v_and_b32_e32 v47, 64, v132
	v_cmp_eq_u32_e64 s[74:75], 0, v46
	v_cmp_eq_u32_e64 s[48:49], 0, v47
	v_lshrrev_b32_e32 v129, 7, v129
	v_lshrrev_b32_e32 v132, 7, v132
	s_waitcnt lgkmcnt(0)
; __device__ __forceinline__ void phase_expert(CArgs& A, int l, unsigned char* lds, int tid, bool dry = false) {
;     ...
;         { float xf[16]; const bf16* xr = X + (size_t)t * DM + lane * 4;
; #pragma unroll
;           for (int i = 0; i < 4; ++i) { const u32x2 v = *(const u32x2*)(xr + 256 * i); xf[4 * i] = __uint_as_float(v.x << 16); xf[4 * i + 1] = __uint_as_float(v.x & 0xffff0000u); xf[4 * i + 2] = __uint_as_float(v.y << 16); xf[4 * i + 3] = __uint_as_float(v.y & 0xffff0000u); }
; #pragma unroll
;           for (int i = 0; i < 8; ++i) { x[i] = (f32x2){xf[2 * i], xf[2 * i + 1]}; ff[i] = (f32x2){0.f, 0.f}; } }
;         const int id0 = IDX[(size_t)t * 128 + lane], id1 = IDX[(size_t)t * 128 + 64 + lane];
;         const float gl0 = GATE[(size_t)t * 128 + lane], gl1 = GATE[(size_t)t * 128 + 64 + lane];
;         float xinv; int xh0 = 0, xh1 = 0, xl0 = 0, xl1 = 0;
;         { float am = 0.f;
; #pragma unroll
;           for (int i = 0; i < 8; ++i) am = fmaxf(am, fmaxf(fabsf(x[i].x), fabsf(x[i].y)));
; #pragma unroll
;           for (int o = 1; o < 64; o <<= 1) am = fmaxf(am, __shfl_xor(am, o));
	v_cndmask_b32_e64 v133, v49, v48, s[74:75]
	v_cndmask_b32_e64 v1, v51, v50, s[48:49]
	v_lshlrev_b32_e32 v156, 16, v34
	v_and_b32_e32 v157, 0xffff0000, v34
	v_lshlrev_b32_e32 v154, 16, v35
	v_and_b32_e32 v155, 0xffff0000, v35
	v_lshlrev_b32_e32 v152, 16, v36
	v_and_b32_e32 v153, 0xffff0000, v36
	v_lshlrev_b32_e32 v150, 16, v37
	v_and_b32_e32 v151, 0xffff0000, v37
	v_max_f32_e64 v34, |v157|, |v157|
	v_max_f32_e64 v35, |v156|, |v156|
	v_max_f32_e64 v36, |v155|, |v155|
	v_max_f32_e64 v37, |v154|, |v154|
	v_lshlrev_b32_e32 v148, 16, v38
	v_and_b32_e32 v149, 0xffff0000, v38
	v_lshlrev_b32_e32 v146, 16, v39
	v_and_b32_e32 v147, 0xffff0000, v39
	v_lshlrev_b32_e32 v144, 16, v40
	v_and_b32_e32 v145, 0xffff0000, v40
	v_lshlrev_b32_e32 v140, 16, v41
	v_and_b32_e32 v141, 0xffff0000, v41
	v_max_f32_e64 v38, |v153|, |v153|
	v_max_f32_e64 v39, |v152|, |v152|
	v_max_f32_e64 v40, |v151|, |v151|
	v_max_f32_e64 v41, |v150|, |v150|
	v_max_f32_e32 v34, v35, v34
	v_max_f32_e32 v35, v37, v36
	v_max_f32_e64 v42, |v149|, |v149|
	v_max_f32_e64 v43, |v148|, |v148|
	v_max_f32_e64 v44, |v147|, |v147|
	v_max_f32_e64 v45, |v146|, |v146|
	v_max_f32_e32 v36, v39, v38
	v_max_f32_e32 v37, v41, v40
	v_max3_f32 v34, v34, 0, v35
	v_max_f32_e64 v46, |v145|, |v145|
	v_max_f32_e64 v47, |v144|, |v144|
	v_max_f32_e64 v48, |v141|, |v141|
	v_max_f32_e64 v49, |v140|, |v140|
	v_max_f32_e32 v38, v43, v42
	v_max_f32_e32 v39, v45, v44
	v_max3_f32 v34, v34, v36, v37
	v_max_f32_e32 v40, v47, v46
	v_max_f32_e32 v41, v49, v48
	v_max3_f32 v34, v34, v38, v39
	v_max3_f32 v34, v34, v40, v41
	ds_bpermute_b32 v35, v143, v34
	s_waitcnt lgkmcnt(0)
	v_max_f32_e32 v35, v35, v35
	v_max_f32_e32 v34, v34, v35
	ds_bpermute_b32 v35, v192, v34
	s_waitcnt lgkmcnt(0)
	v_max_f32_e32 v35, v35, v35
	v_max_f32_e32 v34, v34, v35
	ds_bpermute_b32 v35, v193, v34
	s_waitcnt lgkmcnt(0)
	v_max_f32_e32 v35, v35, v35
	v_max_f32_e32 v34, v34, v35
	ds_bpermute_b32 v35, v194, v34
	s_waitcnt lgkmcnt(0)
	v_max_f32_e32 v35, v35, v35
	v_max_f32_e32 v36, v34, v35
	ds_bpermute_b32 v40, v195, v36
	s_waitcnt lgkmcnt(0)
	v_max_f32_e32 v40, v40, v40
	v_max_f32_e32 v42, v36, v40
	ds_bpermute_b32 v43, v196, v42
	s_waitcnt lgkmcnt(0)
; __device__ __forceinline__ void phase_expert(CArgs& A, int l, unsigned char* lds, int tid, bool dry = false) {
;     ...
;         float xinv; int xh0 = 0, xh1 = 0, xl0 = 0, xl1 = 0;
;         { float am = 0.f;
; #pragma unroll
;           for (int i = 0; i < 8; ++i) am = fmaxf(am, fmaxf(fabsf(x[i].x), fabsf(x[i].y)));
; #pragma unroll
;           for (int o = 1; o < 64; o <<= 1) am = fmaxf(am, __shfl_xor(am, o));
;           const float xs = 119.f / fmaxf(am, 1e-20f); xinv = 1.f / (xs * U_SCALE);
; #pragma unroll
;           for (int i = 0; i < 16; ++i) { const float xv = (i & 1) ? x[i >> 1].y : x[i >> 1].x; const int q = (int)rintf(xv * xs);
;               const int lo = ((q + 8) & 15) - 8, hi = (q - lo) >> 4;
;               if (i < 8) { xl0 |= (lo & 15) << (4 * i); xh0 |= (hi & 15) << (4 * i); } else { xl1 |= (lo & 15) << (4 * (i - 8)); xh1 |= (hi & 15) << (4 * (i - 8)); } } }
;         u32x2 ur[2][8], vr[2][8]; float gtv[2];
	v_max3_f32 v42, v42, v43, s0
	v_div_scale_f32 v43, s[0:1], v42, v42, s4
	v_rcp_f32_e32 v44, v43
	v_div_scale_f32 v34, vcc, s4, v42, s4
	v_fma_f32 v35, -v43, v44, 1.0
	v_fmac_f32_e32 v44, v35, v44
	v_mul_f32_e32 v35, v34, v44
	v_fma_f32 v36, -v43, v35, v34
	v_fmac_f32_e32 v35, v36, v44
	v_fma_f32 v34, -v43, v35, v34
	v_div_fmas_f32 v34, v34, v44, v35
	v_div_fixup_f32 v38, v34, v42, s4
	v_mul_f32_e32 v34, v38, v156
	v_mul_f32_e32 v35, v38, v157
	v_mul_f32_e32 v36, v38, v154
	v_mul_f32_e32 v37, v38, v155
	v_rndne_f32_e32 v34, v34
	v_rndne_f32_e32 v35, v35
	v_rndne_f32_e32 v36, v36
	v_rndne_f32_e32 v37, v37
	v_cvt_i32_f32_e32 v34, v34
	v_cvt_i32_f32_e32 v35, v35
	v_cvt_i32_f32_e32 v36, v36
	v_cvt_i32_f32_e32 v37, v37
	v_mul_f32_e32 v40, v38, v152
	v_mul_f32_e32 v41, v38, v153
	v_rndne_f32_e32 v40, v40
	v_bfe_i32 v44, v34, 0, 4
	v_bfe_i32 v45, v35, 0, 4
	v_bfe_i32 v47, v36, 0, 4
	v_bfe_i32 v49, v37, 0, 4
	v_mul_f32_e32 v42, v38, v150
	v_rndne_f32_e32 v41, v41
	v_cvt_i32_f32_e32 v40, v40
	v_lshlrev_b32_e32 v46, 4, v35
	v_lshlrev_b32_e32 v48, 8, v36
	v_lshlrev_b32_e32 v50, 12, v37
	v_sub_u32_e32 v44, v34, v44
	v_sub_u32_e32 v35, v35, v45
	v_sub_u32_e32 v36, v36, v47
	v_sub_u32_e32 v37, v37, v49
	v_rndne_f32_e32 v42, v42
	v_cvt_i32_f32_e32 v41, v41
	v_lshrrev_b32_e32 v44, 4, v44
	v_and_b32_e32 v35, 0xf0, v35
	v_lshlrev_b32_e32 v36, 4, v36
	v_lshlrev_b32_e32 v37, 8, v37
	v_mul_f32_e32 v43, v38, v151
	v_cvt_i32_f32_e32 v42, v42
	v_and_or_b32 v35, v44, 15, v35
	v_and_b32_e32 v36, 0xf00, v36
	v_and_b32_e32 v37, 0xf000, v37
	v_or3_b32 v35, v35, v36, v37
	v_rndne_f32_e32 v36, v43
	v_bfe_i32 v51, v40, 0, 4
	v_cvt_i32_f32_e32 v36, v36
	v_lshlrev_b32_e32 v52, 16, v40
	v_bfe_i32 v53, v41, 0, 4
	v_sub_u32_e32 v40, v40, v51
	v_lshlrev_b32_e32 v54, 20, v41
	v_bfe_i32 v55, v42, 0, 4
	v_and_b32_e32 v45, 0xf0, v46
	v_sub_u32_sdwa v41, v41, v53 dst_sel:WORD_1 dst_unused:UNUSED_PAD src0_sel:DWORD src1_sel:DWORD
	v_lshlrev_b32_e32 v40, 12, v40
	v_lshlrev_b32_e32 v56, 24, v42
	v_and_b32_e32 v46, 0xf00, v48
	v_and_b32_e32 v47, 0xf000, v50
	v_sub_u32_e32 v42, v42, v55
	v_and_b32_e32 v41, 0xf00000, v41
	v_and_b32_e32 v40, 0xf0000, v40
	v_and_or_b32 v34, v34, 15, v45
	v_and_b32_e32 v48, 0xf0000, v52
	v_and_b32_e32 v49, 0xf00000, v54
	v_or3_b32 v35, v35, v40, v41
	v_lshlrev_b32_e32 v40, 20, v42
	v_bfe_i32 v42, v36, 0, 4
	v_or3_b32 v34, v34, v46, v47
	v_and_b32_e32 v37, 0xf000000, v56
	v_lshlrev_b32_e32 v41, 28, v36
	v_sub_u32_sdwa v36, v36, v42 dst_sel:BYTE_3 dst_unused:UNUSED_PAD src0_sel:DWORD src1_sel:DWORD
	v_or3_b32 v34, v34, v48, v49
	v_and_b32_e32 v40, 0xf000000, v40
	v_or3_b32 v214, v34, v37, v41
	v_and_b32_e32 v34, 0xf0000000, v36
	v_or3_b32 v215, v35, v40, v34
	v_mul_f32_e32 v34, v38, v148
	v_rndne_f32_e32 v34, v34
	v_cvt_i32_f32_e32 v56, v34
	v_mul_f32_e32 v34, v38, v149
	v_rndne_f32_e32 v34, v34
	v_cvt_i32_f32_e32 v34, v34
	v_mul_f32_e32 v37, v38, v146
	v_rndne_f32_e32 v37, v37
	v_cvt_i32_f32_e32 v37, v37
	v_bfe_i32 v35, v56, 0, 4
	v_bfe_i32 v36, v34, 0, 4
	v_sub_u32_e32 v35, v56, v35
	v_sub_u32_e32 v36, v34, v36
	v_lshlrev_b32_e32 v34, 4, v34
	v_lshrrev_b32_e32 v35, 4, v35
	v_and_b32_e32 v57, 0xf0, v34
	v_and_b32_e32 v34, 0xf0, v36
	v_and_or_b32 v74, v35, 15, v34
	v_bfe_i32 v34, v37, 0, 4
	v_sub_u32_e32 v75, v37, v34
	v_lshlrev_b32_e32 v34, 8, v37
	v_and_b32_e32 v76, 0xf00, v34
	v_mul_f32_e32 v34, v38, v147
	v_rndne_f32_e32 v34, v34
	v_cvt_i32_f32_e32 v77, v34
	v_readlane_b32 s11, v210, 16
	s_lshl_b32 s11, s11, 10
	s_add_u32 s48, s72, s11
	s_addc_u32 s49, s73, 0
	global_load_dwordx4 v[40:43], v219, s[48:49]
	v_readlane_b32 s37, v210, 17
	s_lshl_b32 s37, s37, 10
	s_add_u32 s50, s72, s37
	s_addc_u32 s51, s73, 0
	global_load_dwordx4 v[44:47], v219, s[50:51]
	v_readlane_b32 s11, v210, 18
	s_lshl_b32 s11, s11, 10
	s_add_u32 s48, s72, s11
	s_addc_u32 s49, s73, 0
	global_load_dwordx4 v[48:51], v219, s[48:49]
	v_readlane_b32 s37, v210, 19
	s_lshl_b32 s37, s37, 10
	s_add_u32 s50, s72, s37
	s_addc_u32 s51, s73, 0
	global_load_dwordx4 v[52:55], v219, s[50:51]
	v_readlane_b32 s11, v210, 20
	s_lshl_b32 s11, s11, 10
	s_add_u32 s48, s72, s11
	s_addc_u32 s49, s73, 0
	global_load_dwordx4 v[58:61], v219, s[48:49]
	v_readlane_b32 s37, v210, 21
	s_lshl_b32 s37, s37, 10
	s_add_u32 s50, s72, s37
	s_addc_u32 s51, s73, 0
	global_load_dwordx4 v[62:65], v219, s[50:51]
	v_readlane_b32 s11, v210, 22
	s_lshl_b32 s11, s11, 10
	s_add_u32 s48, s72, s11
	s_addc_u32 s49, s73, 0
	global_load_dwordx4 v[66:69], v219, s[48:49]
	v_readlane_b32 s37, v210, 23
	s_lshl_b32 s37, s37, 10
	s_add_u32 s50, s72, s37
	s_addc_u32 s51, s73, 0
	global_load_dwordx4 v[70:73], v219, s[50:51]
	v_bfe_i32 v35, v77, 0, 4
	v_sub_u32_e32 v35, v77, v35
	v_lshlrev_b32_e32 v34, 4, v75
	v_lshlrev_b32_e32 v35, 8, v35
	v_and_b32_e32 v34, 0xf00, v34
	v_mul_f32_e32 v37, v38, v144
	v_and_b32_e32 v35, 0xf000, v35
	v_rndne_f32_e32 v37, v37
	v_or3_b32 v34, v74, v34, v35
	v_mul_f32_e32 v74, v38, v145
	v_cvt_i32_f32_e32 v37, v37
	v_rndne_f32_e32 v74, v74
	v_cvt_i32_f32_e32 v74, v74
	v_lshlrev_b32_e32 v36, 12, v77
	v_mul_f32_e32 v77, v38, v140
	v_mul_f32_e32 v39, 0x42a00000, v38
	v_rndne_f32_e32 v77, v77
	v_mul_f32_e32 v38, v38, v141
	v_bfe_i32 v35, v37, 0, 4
	v_cvt_i32_f32_e32 v77, v77
	v_rndne_f32_e32 v38, v38
	v_sub_u32_e32 v35, v37, v35
	v_bfe_i32 v75, v74, 0, 4
	v_cvt_i32_f32_e32 v38, v38
	v_lshlrev_b32_e32 v35, 12, v35
	v_sub_u32_sdwa v75, v74, v75 dst_sel:WORD_1 dst_unused:UNUSED_PAD src0_sel:DWORD src1_sel:DWORD
	v_and_b32_e32 v36, 0xf000, v36
	v_lshlrev_b32_e32 v37, 16, v37
	v_and_b32_e32 v35, 0xf0000, v35
	v_lshlrev_b32_e32 v74, 20, v74
	v_and_b32_e32 v75, 0xf00000, v75
	v_and_or_b32 v56, v56, 15, v57
	v_and_b32_e32 v37, 0xf0000, v37
	v_and_b32_e32 v74, 0xf00000, v74
	v_or3_b32 v34, v34, v35, v75
	v_bfe_i32 v35, v77, 0, 4
	v_lshlrev_b32_e32 v75, 24, v77
	v_or3_b32 v36, v56, v76, v36
	v_sub_u32_e32 v35, v77, v35
	v_and_b32_e32 v75, 0xf000000, v75
	v_lshlrev_b32_e32 v77, 28, v38
	v_or3_b32 v36, v36, v37, v74
	v_or3_b32 v216, v36, v75, v77
	v_div_scale_f32 v36, s[0:1], v39, v39, 1.0
	v_rcp_f32_e32 v37, v36
	v_bfe_i32 v78, v38, 0, 4
	v_lshlrev_b32_e32 v35, 20, v35
	v_sub_u32_sdwa v38, v38, v78 dst_sel:BYTE_3 dst_unused:UNUSED_PAD src0_sel:DWORD src1_sel:DWORD
	v_and_b32_e32 v35, 0xf000000, v35
	v_and_b32_e32 v38, 0xf0000000, v38
	v_or3_b32 v217, v34, v35, v38
	v_fma_f32 v34, -v36, v37, 1.0
	v_fmac_f32_e32 v37, v34, v37
	v_div_scale_f32 v34, vcc, 1.0, v39, 1.0
	v_mul_f32_e32 v35, v34, v37
	v_fma_f32 v38, -v36, v35, v34
	v_fmac_f32_e32 v35, v38, v37
	v_fma_f32 v34, -v36, v35, v34
	v_div_fmas_f32 v34, v34, v37, v35
	v_div_fixup_f32 v218, v34, v39, 1.0
	v_mov_b32_e32 v240, 0
	v_mov_b32_e32 v241, 0
	v_mov_b32_e32 v242, 0
	v_mov_b32_e32 v243, 0
	v_mov_b32_e32 v244, 0
	v_mov_b32_e32 v245, 0
	v_mov_b32_e32 v246, 0
	v_mov_b32_e32 v247, 0
	v_mov_b32_e32 v248, 0
	v_mov_b32_e32 v249, 0
	v_mov_b32_e32 v124, 0
	v_mov_b32_e32 v125, 0
	s_mov_b32 s8, 0

; __device__ __forceinline__ float gelu_erf(float x) { return 0.5f * x * (1.f + erff(x * 0.70710678118654752f)); }
.Lpx_g0:
	s_andn2_saveexec_b64 s[4:5], s[4:5]
	v_mul_f32_e32 v76, v75, v75
	v_fmamk_f32 v77, v76, 0xba1345e1, v163
	v_fmaak_f32 v77, v76, v77, 0xbcdac9b8
	v_fmaak_f32 v77, v76, v77, 0x3de703be
	v_fmaak_f32 v77, v76, v77, 0xbec09330
	v_fmaak_f32 v76, v76, v77, 0x3e0375d0
	v_fma_f32 v76, |v75|, v76, |v75|
	s_or_b64 exec, exec, s[4:5]
	v_bfi_b32 v75, s2, v76, v75
	v_mul_f32_e32 v74, 0.5, v74
	v_add_f32_e32 v75, 1.0, v75
	v_mul_f32_e32 v74, v74, v75
	s_sub_i32 s9, s8, 3
	s_cmp_lt_u32 s9, 8
	s_cselect_b64 vcc, -1, 0
	v_cndmask_b32_e32 v76, v1, v133, vcc
	s_cmp_lt_u32 s8, 3
	s_cselect_b64 vcc, -1, 0
	s_cselect_b32 s9, s8, s9
	v_cndmask_b32_e32 v76, v76, v212, vcc
	v_mul_f32_e32 v74, v76, v74
	v_mul_f32_e32 v74, 0x3dba2e8c, v74
	s_lshl_b32 s9, s9, 3
	s_and_b32 s9, s9, 63
	v_readlane_b32 s70, v74, s9
	s_add_i32 s9, s9, 1
	v_readlane_b32 s68, v74, s9
	s_add_i32 s9, s9, 1
	v_readlane_b32 s66, v74, s9
	s_add_i32 s9, s9, 1
	v_readlane_b32 s64, v74, s9
	s_add_i32 s9, s9, 1
	v_readlane_b32 s36, v74, s9
	s_add_i32 s9, s9, 1
	v_readlane_b32 s14, v74, s9
	s_add_i32 s9, s9, 1
	v_readlane_b32 s10, v74, s9
	s_add_i32 s9, s9, 1
	v_readlane_b32 s4, v74, s9
	v_cvt_scalef32_pk_f32_fp4 v[80:81], v82, 1.0
	v_cvt_scalef32_pk_f32_fp4 v[84:85], v82, 1.0 op_sel:[1,0,0]
	v_cvt_scalef32_pk_f32_fp4 v[88:89], v82, 1.0 op_sel:[0,1,0]
	v_cvt_scalef32_pk_f32_fp4 v[92:93], v82, 1.0 op_sel:[1,1,0]
	v_cvt_scalef32_pk_f32_fp4 v[96:97], v83, 1.0
	v_cvt_scalef32_pk_f32_fp4 v[100:101], v83, 1.0 op_sel:[1,0,0]
	v_cvt_scalef32_pk_f32_fp4 v[104:105], v83, 1.0 op_sel:[0,1,0]
	v_cvt_scalef32_pk_f32_fp4 v[108:109], v83, 1.0 op_sel:[1,1,0]
	v_pk_fma_f32 v[158:159], v[80:81], s[70:71], v[158:159] op_sel_hi:[1,0,1]
	v_pk_fma_f32 v[160:161], v[84:85], s[70:71], v[160:161] op_sel_hi:[1,0,1]
	v_pk_fma_f32 v[240:241], v[88:89], s[70:71], v[240:241] op_sel_hi:[1,0,1]
	v_pk_fma_f32 v[242:243], v[92:93], s[70:71], v[242:243] op_sel_hi:[1,0,1]
	v_pk_fma_f32 v[244:245], v[96:97], s[70:71], v[244:245] op_sel_hi:[1,0,1]
	v_pk_fma_f32 v[246:247], v[100:101], s[70:71], v[246:247] op_sel_hi:[1,0,1]
	v_pk_fma_f32 v[248:249], v[104:105], s[70:71], v[248:249] op_sel_hi:[1,0,1]
	v_pk_fma_f32 v[124:125], v[108:109], s[70:71], v[124:125] op_sel_hi:[1,0,1]
	v_cvt_scalef32_pk_f32_fp4 v[80:81], v86, 1.0
	v_cvt_scalef32_pk_f32_fp4 v[84:85], v86, 1.0 op_sel:[1,0,0]
	v_cvt_scalef32_pk_f32_fp4 v[88:89], v86, 1.0 op_sel:[0,1,0]
	v_cvt_scalef32_pk_f32_fp4 v[92:93], v86, 1.0 op_sel:[1,1,0]
	v_cvt_scalef32_pk_f32_fp4 v[96:97], v87, 1.0
	v_cvt_scalef32_pk_f32_fp4 v[100:101], v87, 1.0 op_sel:[1,0,0]
	v_cvt_scalef32_pk_f32_fp4 v[104:105], v87, 1.0 op_sel:[0,1,0]
	v_cvt_scalef32_pk_f32_fp4 v[108:109], v87, 1.0 op_sel:[1,1,0]
	v_pk_fma_f32 v[158:159], v[80:81], s[68:69], v[158:159] op_sel_hi:[1,0,1]
	v_pk_fma_f32 v[160:161], v[84:85], s[68:69], v[160:161] op_sel_hi:[1,0,1]
	v_pk_fma_f32 v[240:241], v[88:89], s[68:69], v[240:241] op_sel_hi:[1,0,1]
	v_pk_fma_f32 v[242:243], v[92:93], s[68:69], v[242:243] op_sel_hi:[1,0,1]
	v_pk_fma_f32 v[244:245], v[96:97], s[68:69], v[244:245] op_sel_hi:[1,0,1]
	v_pk_fma_f32 v[246:247], v[100:101], s[68:69], v[246:247] op_sel_hi:[1,0,1]
	v_pk_fma_f32 v[248:249], v[104:105], s[68:69], v[248:249] op_sel_hi:[1,0,1]
	v_pk_fma_f32 v[124:125], v[108:109], s[68:69], v[124:125] op_sel_hi:[1,0,1]
	v_cvt_scalef32_pk_f32_fp4 v[80:81], v90, 1.0
	v_cvt_scalef32_pk_f32_fp4 v[84:85], v90, 1.0 op_sel:[1,0,0]
	v_cvt_scalef32_pk_f32_fp4 v[88:89], v90, 1.0 op_sel:[0,1,0]
	v_cvt_scalef32_pk_f32_fp4 v[92:93], v90, 1.0 op_sel:[1,1,0]
	v_cvt_scalef32_pk_f32_fp4 v[96:97], v91, 1.0
	v_cvt_scalef32_pk_f32_fp4 v[100:101], v91, 1.0 op_sel:[1,0,0]
	v_cvt_scalef32_pk_f32_fp4 v[104:105], v91, 1.0 op_sel:[0,1,0]
	v_cvt_scalef32_pk_f32_fp4 v[108:109], v91, 1.0 op_sel:[1,1,0]
	v_pk_fma_f32 v[158:159], v[80:81], s[66:67], v[158:159] op_sel_hi:[1,0,1]
	v_pk_fma_f32 v[160:161], v[84:85], s[66:67], v[160:161] op_sel_hi:[1,0,1]
	v_pk_fma_f32 v[240:241], v[88:89], s[66:67], v[240:241] op_sel_hi:[1,0,1]
	v_pk_fma_f32 v[242:243], v[92:93], s[66:67], v[242:243] op_sel_hi:[1,0,1]
	v_pk_fma_f32 v[244:245], v[96:97], s[66:67], v[244:245] op_sel_hi:[1,0,1]
	v_pk_fma_f32 v[246:247], v[100:101], s[66:67], v[246:247] op_sel_hi:[1,0,1]
	v_pk_fma_f32 v[248:249], v[104:105], s[66:67], v[248:249] op_sel_hi:[1,0,1]
	v_pk_fma_f32 v[124:125], v[108:109], s[66:67], v[124:125] op_sel_hi:[1,0,1]
	v_cvt_scalef32_pk_f32_fp4 v[80:81], v94, 1.0
	v_cvt_scalef32_pk_f32_fp4 v[84:85], v94, 1.0 op_sel:[1,0,0]
	v_cvt_scalef32_pk_f32_fp4 v[88:89], v94, 1.0 op_sel:[0,1,0]
	v_cvt_scalef32_pk_f32_fp4 v[92:93], v94, 1.0 op_sel:[1,1,0]
	v_cvt_scalef32_pk_f32_fp4 v[96:97], v95, 1.0
	v_cvt_scalef32_pk_f32_fp4 v[100:101], v95, 1.0 op_sel:[1,0,0]
	v_cvt_scalef32_pk_f32_fp4 v[104:105], v95, 1.0 op_sel:[0,1,0]
	v_cvt_scalef32_pk_f32_fp4 v[108:109], v95, 1.0 op_sel:[1,1,0]
	v_pk_fma_f32 v[158:159], v[80:81], s[64:65], v[158:159] op_sel_hi:[1,0,1]
	v_pk_fma_f32 v[160:161], v[84:85], s[64:65], v[160:161] op_sel_hi:[1,0,1]
	v_pk_fma_f32 v[240:241], v[88:89], s[64:65], v[240:241] op_sel_hi:[1,0,1]
	v_pk_fma_f32 v[242:243], v[92:93], s[64:65], v[242:243] op_sel_hi:[1,0,1]
	v_pk_fma_f32 v[244:245], v[96:97], s[64:65], v[244:245] op_sel_hi:[1,0,1]
	v_pk_fma_f32 v[246:247], v[100:101], s[64:65], v[246:247] op_sel_hi:[1,0,1]
	v_pk_fma_f32 v[248:249], v[104:105], s[64:65], v[248:249] op_sel_hi:[1,0,1]
	v_pk_fma_f32 v[124:125], v[108:109], s[64:65], v[124:125] op_sel_hi:[1,0,1]
	v_cvt_scalef32_pk_f32_fp4 v[80:81], v98, 1.0
	v_cvt_scalef32_pk_f32_fp4 v[84:85], v98, 1.0 op_sel:[1,0,0]
	v_cvt_scalef32_pk_f32_fp4 v[88:89], v98, 1.0 op_sel:[0,1,0]
	v_cvt_scalef32_pk_f32_fp4 v[92:93], v98, 1.0 op_sel:[1,1,0]
; __device__ __forceinline__ void phase_expert(CArgs& A, int l, unsigned char* lds, int tid, bool dry = false) {
;     ...
;         PEER_LOAD(0, 0);
; #pragma unroll 1
;         for (int c2 = 0; c2 < 8; ++c2) {
;             PEER_LOAD(1, 2 * c2 + 1);
;             PEER_COMPUTE(0);
;             if (c2 < 7) PEER_LOAD(0, 2 * c2 + 2);
	v_cvt_scalef32_pk_f32_fp4 v[96:97], v99, 1.0
	v_cvt_scalef32_pk_f32_fp4 v[100:101], v99, 1.0 op_sel:[1,0,0]
	v_cvt_scalef32_pk_f32_fp4 v[104:105], v99, 1.0 op_sel:[0,1,0]
	v_cvt_scalef32_pk_f32_fp4 v[108:109], v99, 1.0 op_sel:[1,1,0]
	v_pk_fma_f32 v[158:159], v[80:81], s[36:37], v[158:159] op_sel_hi:[1,0,1]
	v_pk_fma_f32 v[160:161], v[84:85], s[36:37], v[160:161] op_sel_hi:[1,0,1]
	v_pk_fma_f32 v[240:241], v[88:89], s[36:37], v[240:241] op_sel_hi:[1,0,1]
	v_pk_fma_f32 v[242:243], v[92:93], s[36:37], v[242:243] op_sel_hi:[1,0,1]
	v_pk_fma_f32 v[244:245], v[96:97], s[36:37], v[244:245] op_sel_hi:[1,0,1]
	v_pk_fma_f32 v[246:247], v[100:101], s[36:37], v[246:247] op_sel_hi:[1,0,1]
	v_pk_fma_f32 v[248:249], v[104:105], s[36:37], v[248:249] op_sel_hi:[1,0,1]
	v_pk_fma_f32 v[124:125], v[108:109], s[36:37], v[124:125] op_sel_hi:[1,0,1]
	v_cvt_scalef32_pk_f32_fp4 v[80:81], v102, 1.0
	v_cvt_scalef32_pk_f32_fp4 v[84:85], v102, 1.0 op_sel:[1,0,0]
	v_cvt_scalef32_pk_f32_fp4 v[88:89], v102, 1.0 op_sel:[0,1,0]
	v_cvt_scalef32_pk_f32_fp4 v[92:93], v102, 1.0 op_sel:[1,1,0]
	v_cvt_scalef32_pk_f32_fp4 v[96:97], v103, 1.0
	v_cvt_scalef32_pk_f32_fp4 v[100:101], v103, 1.0 op_sel:[1,0,0]
	v_cvt_scalef32_pk_f32_fp4 v[104:105], v103, 1.0 op_sel:[0,1,0]
	v_cvt_scalef32_pk_f32_fp4 v[108:109], v103, 1.0 op_sel:[1,1,0]
	v_pk_fma_f32 v[158:159], v[80:81], s[14:15], v[158:159] op_sel_hi:[1,0,1]
	v_pk_fma_f32 v[160:161], v[84:85], s[14:15], v[160:161] op_sel_hi:[1,0,1]
	v_pk_fma_f32 v[240:241], v[88:89], s[14:15], v[240:241] op_sel_hi:[1,0,1]
	v_pk_fma_f32 v[242:243], v[92:93], s[14:15], v[242:243] op_sel_hi:[1,0,1]
	v_pk_fma_f32 v[244:245], v[96:97], s[14:15], v[244:245] op_sel_hi:[1,0,1]
	v_pk_fma_f32 v[246:247], v[100:101], s[14:15], v[246:247] op_sel_hi:[1,0,1]
	v_pk_fma_f32 v[248:249], v[104:105], s[14:15], v[248:249] op_sel_hi:[1,0,1]
	v_pk_fma_f32 v[124:125], v[108:109], s[14:15], v[124:125] op_sel_hi:[1,0,1]
	v_cvt_scalef32_pk_f32_fp4 v[80:81], v106, 1.0
	v_cvt_scalef32_pk_f32_fp4 v[84:85], v106, 1.0 op_sel:[1,0,0]
	v_cvt_scalef32_pk_f32_fp4 v[88:89], v106, 1.0 op_sel:[0,1,0]
	v_cvt_scalef32_pk_f32_fp4 v[92:93], v106, 1.0 op_sel:[1,1,0]
	v_cvt_scalef32_pk_f32_fp4 v[96:97], v107, 1.0
	v_cvt_scalef32_pk_f32_fp4 v[100:101], v107, 1.0 op_sel:[1,0,0]
	v_cvt_scalef32_pk_f32_fp4 v[104:105], v107, 1.0 op_sel:[0,1,0]
	v_cvt_scalef32_pk_f32_fp4 v[108:109], v107, 1.0 op_sel:[1,1,0]
	v_pk_fma_f32 v[158:159], v[80:81], s[10:11], v[158:159] op_sel_hi:[1,0,1]
	v_pk_fma_f32 v[160:161], v[84:85], s[10:11], v[160:161] op_sel_hi:[1,0,1]
	v_pk_fma_f32 v[240:241], v[88:89], s[10:11], v[240:241] op_sel_hi:[1,0,1]
	v_pk_fma_f32 v[242:243], v[92:93], s[10:11], v[242:243] op_sel_hi:[1,0,1]
	v_pk_fma_f32 v[244:245], v[96:97], s[10:11], v[244:245] op_sel_hi:[1,0,1]
	v_pk_fma_f32 v[246:247], v[100:101], s[10:11], v[246:247] op_sel_hi:[1,0,1]
	v_pk_fma_f32 v[248:249], v[104:105], s[10:11], v[248:249] op_sel_hi:[1,0,1]
	v_pk_fma_f32 v[124:125], v[108:109], s[10:11], v[124:125] op_sel_hi:[1,0,1]
	v_cvt_scalef32_pk_f32_fp4 v[80:81], v110, 1.0
	v_cvt_scalef32_pk_f32_fp4 v[84:85], v110, 1.0 op_sel:[1,0,0]
	v_cvt_scalef32_pk_f32_fp4 v[88:89], v110, 1.0 op_sel:[0,1,0]
	v_cvt_scalef32_pk_f32_fp4 v[92:93], v110, 1.0 op_sel:[1,1,0]
	v_cvt_scalef32_pk_f32_fp4 v[96:97], v111, 1.0
	v_cvt_scalef32_pk_f32_fp4 v[100:101], v111, 1.0 op_sel:[1,0,0]
	v_cvt_scalef32_pk_f32_fp4 v[104:105], v111, 1.0 op_sel:[0,1,0]
	v_cvt_scalef32_pk_f32_fp4 v[108:109], v111, 1.0 op_sel:[1,1,0]
	v_pk_fma_f32 v[158:159], v[80:81], s[4:5], v[158:159] op_sel_hi:[1,0,1]
	v_pk_fma_f32 v[160:161], v[84:85], s[4:5], v[160:161] op_sel_hi:[1,0,1]
	v_pk_fma_f32 v[240:241], v[88:89], s[4:5], v[240:241] op_sel_hi:[1,0,1]
	v_pk_fma_f32 v[242:243], v[92:93], s[4:5], v[242:243] op_sel_hi:[1,0,1]
	v_pk_fma_f32 v[244:245], v[96:97], s[4:5], v[244:245] op_sel_hi:[1,0,1]
	v_pk_fma_f32 v[246:247], v[100:101], s[4:5], v[246:247] op_sel_hi:[1,0,1]
	v_pk_fma_f32 v[248:249], v[104:105], s[4:5], v[248:249] op_sel_hi:[1,0,1]
	v_pk_fma_f32 v[124:125], v[108:109], s[4:5], v[124:125] op_sel_hi:[1,0,1]
	s_cmp_eq_u32 s8, 15
	s_cbranch_scc1 .Lpx_done
	s_add_i32 s0, s8, 3
	s_cmp_gt_u32 s0, 15
	s_cbranch_scc1 .Lpx_sk0
	s_cmp_lt_u32 s8, 8
	s_cselect_b64 vcc, -1, 0
	v_cndmask_b32_e32 v76, v132, v129, vcc
	s_lshl_b32 s9, s8, 3
	s_and_b32 s9, s9, 63
	v_readlane_b32 s11, v76, s9
	s_add_i32 s9, s9, 1
	s_lshl_b32 s11, s11, 10
	s_add_u32 s48, s72, s11
	s_addc_u32 s49, s73, 0
	global_load_dwordx4 v[80:83], v219, s[48:49]
	v_readlane_b32 s37, v76, s9
	s_add_i32 s9, s9, 1
	s_lshl_b32 s37, s37, 10
	s_add_u32 s50, s72, s37
	s_addc_u32 s51, s73, 0
	global_load_dwordx4 v[84:87], v219, s[50:51]
	v_readlane_b32 s11, v76, s9
	s_add_i32 s9, s9, 1
	s_lshl_b32 s11, s11, 10
	s_add_u32 s48, s72, s11
	s_addc_u32 s49, s73, 0
	global_load_dwordx4 v[88:91], v219, s[48:49]
	v_readlane_b32 s37, v76, s9
	s_add_i32 s9, s9, 1
	s_lshl_b32 s37, s37, 10
	s_add_u32 s50, s72, s37
	s_addc_u32 s51, s73, 0
	global_load_dwordx4 v[92:95], v219, s[50:51]
	v_readlane_b32 s11, v76, s9
	s_add_i32 s9, s9, 1
	s_lshl_b32 s11, s11, 10
	s_add_u32 s48, s72, s11
	s_addc_u32 s49, s73, 0
	global_load_dwordx4 v[96:99], v219, s[48:49]
	v_readlane_b32 s37, v76, s9
	s_add_i32 s9, s9, 1
	s_lshl_b32 s37, s37, 10
	s_add_u32 s50, s72, s37
	s_addc_u32 s51, s73, 0
	global_load_dwordx4 v[100:103], v219, s[50:51]
	v_readlane_b32 s11, v76, s9
	s_add_i32 s9, s9, 1
	s_lshl_b32 s11, s11, 10
	s_add_u32 s48, s72, s11
	s_addc_u32 s49, s73, 0
	global_load_dwordx4 v[104:107], v219, s[48:49]
	v_readlane_b32 s37, v76, s9
	s_lshl_b32 s37, s37, 10
	s_add_u32 s50, s72, s37
	s_addc_u32 s51, s73, 0
	global_load_dwordx4 v[108:111], v219, s[50:51]

; __device__ __forceinline__ float gelu_erf(float x) { return 0.5f * x * (1.f + erff(x * 0.70710678118654752f)); }
.Lpx_g1:
	s_andn2_saveexec_b64 s[4:5], s[4:5]
	v_mul_f32_e32 v76, v75, v75
	v_fmamk_f32 v77, v76, 0xba1345e1, v163
	v_fmaak_f32 v77, v76, v77, 0xbcdac9b8
	v_fmaak_f32 v77, v76, v77, 0x3de703be
	v_fmaak_f32 v77, v76, v77, 0xbec09330
	v_fmaak_f32 v76, v76, v77, 0x3e0375d0
	v_fma_f32 v76, |v75|, v76, |v75|
	s_or_b64 exec, exec, s[4:5]
	v_bfi_b32 v75, s2, v76, v75
	v_mul_f32_e32 v74, 0.5, v74
	v_add_f32_e32 v75, 1.0, v75
	v_mul_f32_e32 v74, v74, v75
	s_sub_i32 s9, s8, 3
	s_cmp_lt_u32 s9, 8
	s_cselect_b64 vcc, -1, 0
	v_cndmask_b32_e32 v76, v1, v133, vcc
	s_cmp_lt_u32 s8, 3
	s_cselect_b64 vcc, -1, 0
	s_cselect_b32 s9, s8, s9
	v_cndmask_b32_e32 v76, v76, v212, vcc
	v_mul_f32_e32 v74, v76, v74
	v_mul_f32_e32 v74, 0x3dba2e8c, v74
	s_lshl_b32 s9, s9, 3
	s_and_b32 s9, s9, 63
	v_readlane_b32 s70, v74, s9
	s_add_i32 s9, s9, 1
	v_readlane_b32 s68, v74, s9
	s_add_i32 s9, s9, 1
	v_readlane_b32 s66, v74, s9
	s_add_i32 s9, s9, 1
	v_readlane_b32 s64, v74, s9
	s_add_i32 s9, s9, 1
	v_readlane_b32 s36, v74, s9
	s_add_i32 s9, s9, 1
	v_readlane_b32 s14, v74, s9
	s_add_i32 s9, s9, 1
	v_readlane_b32 s10, v74, s9
	s_add_i32 s9, s9, 1
	v_readlane_b32 s4, v74, s9
	v_cvt_scalef32_pk_f32_fp4 v[112:113], v114, 1.0
	v_cvt_scalef32_pk_f32_fp4 v[116:117], v114, 1.0 op_sel:[1,0,0]
	v_cvt_scalef32_pk_f32_fp4 v[120:121], v114, 1.0 op_sel:[0,1,0]
	v_cvt_scalef32_pk_f32_fp4 v[220:221], v114, 1.0 op_sel:[1,1,0]
	v_cvt_scalef32_pk_f32_fp4 v[224:225], v115, 1.0
	v_cvt_scalef32_pk_f32_fp4 v[228:229], v115, 1.0 op_sel:[1,0,0]
	v_cvt_scalef32_pk_f32_fp4 v[232:233], v115, 1.0 op_sel:[0,1,0]
	v_cvt_scalef32_pk_f32_fp4 v[236:237], v115, 1.0 op_sel:[1,1,0]
	v_pk_fma_f32 v[158:159], v[112:113], s[70:71], v[158:159] op_sel_hi:[1,0,1]
	v_pk_fma_f32 v[160:161], v[116:117], s[70:71], v[160:161] op_sel_hi:[1,0,1]
	v_pk_fma_f32 v[240:241], v[120:121], s[70:71], v[240:241] op_sel_hi:[1,0,1]
	v_pk_fma_f32 v[242:243], v[220:221], s[70:71], v[242:243] op_sel_hi:[1,0,1]
	v_pk_fma_f32 v[244:245], v[224:225], s[70:71], v[244:245] op_sel_hi:[1,0,1]
	v_pk_fma_f32 v[246:247], v[228:229], s[70:71], v[246:247] op_sel_hi:[1,0,1]
	v_pk_fma_f32 v[248:249], v[232:233], s[70:71], v[248:249] op_sel_hi:[1,0,1]
	v_pk_fma_f32 v[124:125], v[236:237], s[70:71], v[124:125] op_sel_hi:[1,0,1]
	v_cvt_scalef32_pk_f32_fp4 v[112:113], v118, 1.0
	v_cvt_scalef32_pk_f32_fp4 v[116:117], v118, 1.0 op_sel:[1,0,0]
	v_cvt_scalef32_pk_f32_fp4 v[120:121], v118, 1.0 op_sel:[0,1,0]
	v_cvt_scalef32_pk_f32_fp4 v[220:221], v118, 1.0 op_sel:[1,1,0]
	v_cvt_scalef32_pk_f32_fp4 v[224:225], v119, 1.0
	v_cvt_scalef32_pk_f32_fp4 v[228:229], v119, 1.0 op_sel:[1,0,0]
	v_cvt_scalef32_pk_f32_fp4 v[232:233], v119, 1.0 op_sel:[0,1,0]
	v_cvt_scalef32_pk_f32_fp4 v[236:237], v119, 1.0 op_sel:[1,1,0]
	v_pk_fma_f32 v[158:159], v[112:113], s[68:69], v[158:159] op_sel_hi:[1,0,1]
	v_pk_fma_f32 v[160:161], v[116:117], s[68:69], v[160:161] op_sel_hi:[1,0,1]
	v_pk_fma_f32 v[240:241], v[120:121], s[68:69], v[240:241] op_sel_hi:[1,0,1]
	v_pk_fma_f32 v[242:243], v[220:221], s[68:69], v[242:243] op_sel_hi:[1,0,1]
	v_pk_fma_f32 v[244:245], v[224:225], s[68:69], v[244:245] op_sel_hi:[1,0,1]
	v_pk_fma_f32 v[246:247], v[228:229], s[68:69], v[246:247] op_sel_hi:[1,0,1]
	v_pk_fma_f32 v[248:249], v[232:233], s[68:69], v[248:249] op_sel_hi:[1,0,1]
	v_pk_fma_f32 v[124:125], v[236:237], s[68:69], v[124:125] op_sel_hi:[1,0,1]
	v_cvt_scalef32_pk_f32_fp4 v[112:113], v122, 1.0
	v_cvt_scalef32_pk_f32_fp4 v[116:117], v122, 1.0 op_sel:[1,0,0]
	v_cvt_scalef32_pk_f32_fp4 v[120:121], v122, 1.0 op_sel:[0,1,0]
	v_cvt_scalef32_pk_f32_fp4 v[220:221], v122, 1.0 op_sel:[1,1,0]
	v_cvt_scalef32_pk_f32_fp4 v[224:225], v123, 1.0
	v_cvt_scalef32_pk_f32_fp4 v[228:229], v123, 1.0 op_sel:[1,0,0]
	v_cvt_scalef32_pk_f32_fp4 v[232:233], v123, 1.0 op_sel:[0,1,0]
	v_cvt_scalef32_pk_f32_fp4 v[236:237], v123, 1.0 op_sel:[1,1,0]
	v_pk_fma_f32 v[158:159], v[112:113], s[66:67], v[158:159] op_sel_hi:[1,0,1]
	v_pk_fma_f32 v[160:161], v[116:117], s[66:67], v[160:161] op_sel_hi:[1,0,1]
	v_pk_fma_f32 v[240:241], v[120:121], s[66:67], v[240:241] op_sel_hi:[1,0,1]
	v_pk_fma_f32 v[242:243], v[220:221], s[66:67], v[242:243] op_sel_hi:[1,0,1]
	v_pk_fma_f32 v[244:245], v[224:225], s[66:67], v[244:245] op_sel_hi:[1,0,1]
	v_pk_fma_f32 v[246:247], v[228:229], s[66:67], v[246:247] op_sel_hi:[1,0,1]
	v_pk_fma_f32 v[248:249], v[232:233], s[66:67], v[248:249] op_sel_hi:[1,0,1]
	v_pk_fma_f32 v[124:125], v[236:237], s[66:67], v[124:125] op_sel_hi:[1,0,1]
	v_cvt_scalef32_pk_f32_fp4 v[112:113], v222, 1.0
	v_cvt_scalef32_pk_f32_fp4 v[116:117], v222, 1.0 op_sel:[1,0,0]
	v_cvt_scalef32_pk_f32_fp4 v[120:121], v222, 1.0 op_sel:[0,1,0]
	v_cvt_scalef32_pk_f32_fp4 v[220:221], v222, 1.0 op_sel:[1,1,0]
	v_cvt_scalef32_pk_f32_fp4 v[224:225], v223, 1.0
	v_cvt_scalef32_pk_f32_fp4 v[228:229], v223, 1.0 op_sel:[1,0,0]
	v_cvt_scalef32_pk_f32_fp4 v[232:233], v223, 1.0 op_sel:[0,1,0]
	v_cvt_scalef32_pk_f32_fp4 v[236:237], v223, 1.0 op_sel:[1,1,0]
	v_pk_fma_f32 v[158:159], v[112:113], s[64:65], v[158:159] op_sel_hi:[1,0,1]
	v_pk_fma_f32 v[160:161], v[116:117], s[64:65], v[160:161] op_sel_hi:[1,0,1]
	v_pk_fma_f32 v[240:241], v[120:121], s[64:65], v[240:241] op_sel_hi:[1,0,1]
	v_pk_fma_f32 v[242:243], v[220:221], s[64:65], v[242:243] op_sel_hi:[1,0,1]
	v_pk_fma_f32 v[244:245], v[224:225], s[64:65], v[244:245] op_sel_hi:[1,0,1]
	v_pk_fma_f32 v[246:247], v[228:229], s[64:65], v[246:247] op_sel_hi:[1,0,1]
	v_pk_fma_f32 v[248:249], v[232:233], s[64:65], v[248:249] op_sel_hi:[1,0,1]
	v_pk_fma_f32 v[124:125], v[236:237], s[64:65], v[124:125] op_sel_hi:[1,0,1]
	v_cvt_scalef32_pk_f32_fp4 v[112:113], v226, 1.0
	v_cvt_scalef32_pk_f32_fp4 v[116:117], v226, 1.0 op_sel:[1,0,0]
; __device__ __forceinline__ void phase_expert(CArgs& A, int l, unsigned char* lds, int tid, bool dry = false) {
;     ...
;         PEER_LOAD(0, 0);
; #pragma unroll 1
;         for (int c2 = 0; c2 < 8; ++c2) {
;             PEER_LOAD(1, 2 * c2 + 1);
;             PEER_COMPUTE(0);
;             if (c2 < 7) PEER_LOAD(0, 2 * c2 + 2);
	v_cvt_scalef32_pk_f32_fp4 v[120:121], v226, 1.0 op_sel:[0,1,0]
	v_cvt_scalef32_pk_f32_fp4 v[220:221], v226, 1.0 op_sel:[1,1,0]
	v_cvt_scalef32_pk_f32_fp4 v[224:225], v227, 1.0
	v_cvt_scalef32_pk_f32_fp4 v[228:229], v227, 1.0 op_sel:[1,0,0]
	v_cvt_scalef32_pk_f32_fp4 v[232:233], v227, 1.0 op_sel:[0,1,0]
	v_cvt_scalef32_pk_f32_fp4 v[236:237], v227, 1.0 op_sel:[1,1,0]
	v_pk_fma_f32 v[158:159], v[112:113], s[36:37], v[158:159] op_sel_hi:[1,0,1]
	v_pk_fma_f32 v[160:161], v[116:117], s[36:37], v[160:161] op_sel_hi:[1,0,1]
	v_pk_fma_f32 v[240:241], v[120:121], s[36:37], v[240:241] op_sel_hi:[1,0,1]
	v_pk_fma_f32 v[242:243], v[220:221], s[36:37], v[242:243] op_sel_hi:[1,0,1]
	v_pk_fma_f32 v[244:245], v[224:225], s[36:37], v[244:245] op_sel_hi:[1,0,1]
	v_pk_fma_f32 v[246:247], v[228:229], s[36:37], v[246:247] op_sel_hi:[1,0,1]
	v_pk_fma_f32 v[248:249], v[232:233], s[36:37], v[248:249] op_sel_hi:[1,0,1]
	v_pk_fma_f32 v[124:125], v[236:237], s[36:37], v[124:125] op_sel_hi:[1,0,1]
	v_cvt_scalef32_pk_f32_fp4 v[112:113], v230, 1.0
	v_cvt_scalef32_pk_f32_fp4 v[116:117], v230, 1.0 op_sel:[1,0,0]
	v_cvt_scalef32_pk_f32_fp4 v[120:121], v230, 1.0 op_sel:[0,1,0]
	v_cvt_scalef32_pk_f32_fp4 v[220:221], v230, 1.0 op_sel:[1,1,0]
	v_cvt_scalef32_pk_f32_fp4 v[224:225], v231, 1.0
	v_cvt_scalef32_pk_f32_fp4 v[228:229], v231, 1.0 op_sel:[1,0,0]
	v_cvt_scalef32_pk_f32_fp4 v[232:233], v231, 1.0 op_sel:[0,1,0]
	v_cvt_scalef32_pk_f32_fp4 v[236:237], v231, 1.0 op_sel:[1,1,0]
	v_pk_fma_f32 v[158:159], v[112:113], s[14:15], v[158:159] op_sel_hi:[1,0,1]
	v_pk_fma_f32 v[160:161], v[116:117], s[14:15], v[160:161] op_sel_hi:[1,0,1]
	v_pk_fma_f32 v[240:241], v[120:121], s[14:15], v[240:241] op_sel_hi:[1,0,1]
	v_pk_fma_f32 v[242:243], v[220:221], s[14:15], v[242:243] op_sel_hi:[1,0,1]
	v_pk_fma_f32 v[244:245], v[224:225], s[14:15], v[244:245] op_sel_hi:[1,0,1]
	v_pk_fma_f32 v[246:247], v[228:229], s[14:15], v[246:247] op_sel_hi:[1,0,1]
	v_pk_fma_f32 v[248:249], v[232:233], s[14:15], v[248:249] op_sel_hi:[1,0,1]
	v_pk_fma_f32 v[124:125], v[236:237], s[14:15], v[124:125] op_sel_hi:[1,0,1]
	v_cvt_scalef32_pk_f32_fp4 v[112:113], v234, 1.0
	v_cvt_scalef32_pk_f32_fp4 v[116:117], v234, 1.0 op_sel:[1,0,0]
	v_cvt_scalef32_pk_f32_fp4 v[120:121], v234, 1.0 op_sel:[0,1,0]
	v_cvt_scalef32_pk_f32_fp4 v[220:221], v234, 1.0 op_sel:[1,1,0]
	v_cvt_scalef32_pk_f32_fp4 v[224:225], v235, 1.0
	v_cvt_scalef32_pk_f32_fp4 v[228:229], v235, 1.0 op_sel:[1,0,0]
	v_cvt_scalef32_pk_f32_fp4 v[232:233], v235, 1.0 op_sel:[0,1,0]
	v_cvt_scalef32_pk_f32_fp4 v[236:237], v235, 1.0 op_sel:[1,1,0]
	v_pk_fma_f32 v[158:159], v[112:113], s[10:11], v[158:159] op_sel_hi:[1,0,1]
	v_pk_fma_f32 v[160:161], v[116:117], s[10:11], v[160:161] op_sel_hi:[1,0,1]
	v_pk_fma_f32 v[240:241], v[120:121], s[10:11], v[240:241] op_sel_hi:[1,0,1]
	v_pk_fma_f32 v[242:243], v[220:221], s[10:11], v[242:243] op_sel_hi:[1,0,1]
	v_pk_fma_f32 v[244:245], v[224:225], s[10:11], v[244:245] op_sel_hi:[1,0,1]
	v_pk_fma_f32 v[246:247], v[228:229], s[10:11], v[246:247] op_sel_hi:[1,0,1]
	v_pk_fma_f32 v[248:249], v[232:233], s[10:11], v[248:249] op_sel_hi:[1,0,1]
	v_pk_fma_f32 v[124:125], v[236:237], s[10:11], v[124:125] op_sel_hi:[1,0,1]
	v_cvt_scalef32_pk_f32_fp4 v[112:113], v238, 1.0
	v_cvt_scalef32_pk_f32_fp4 v[116:117], v238, 1.0 op_sel:[1,0,0]
	v_cvt_scalef32_pk_f32_fp4 v[120:121], v238, 1.0 op_sel:[0,1,0]
	v_cvt_scalef32_pk_f32_fp4 v[220:221], v238, 1.0 op_sel:[1,1,0]
	v_cvt_scalef32_pk_f32_fp4 v[224:225], v239, 1.0
	v_cvt_scalef32_pk_f32_fp4 v[228:229], v239, 1.0 op_sel:[1,0,0]
	v_cvt_scalef32_pk_f32_fp4 v[232:233], v239, 1.0 op_sel:[0,1,0]
	v_cvt_scalef32_pk_f32_fp4 v[236:237], v239, 1.0 op_sel:[1,1,0]
	v_pk_fma_f32 v[158:159], v[112:113], s[4:5], v[158:159] op_sel_hi:[1,0,1]
	v_pk_fma_f32 v[160:161], v[116:117], s[4:5], v[160:161] op_sel_hi:[1,0,1]
	v_pk_fma_f32 v[240:241], v[120:121], s[4:5], v[240:241] op_sel_hi:[1,0,1]
	v_pk_fma_f32 v[242:243], v[220:221], s[4:5], v[242:243] op_sel_hi:[1,0,1]
	v_pk_fma_f32 v[244:245], v[224:225], s[4:5], v[244:245] op_sel_hi:[1,0,1]
	v_pk_fma_f32 v[246:247], v[228:229], s[4:5], v[246:247] op_sel_hi:[1,0,1]
	v_pk_fma_f32 v[248:249], v[232:233], s[4:5], v[248:249] op_sel_hi:[1,0,1]
	v_pk_fma_f32 v[124:125], v[236:237], s[4:5], v[124:125] op_sel_hi:[1,0,1]
	s_add_i32 s0, s8, 3
	s_cmp_gt_u32 s0, 15
	s_cbranch_scc1 .Lpx_sk1
	s_cmp_lt_u32 s8, 8
	s_cselect_b64 vcc, -1, 0
	v_cndmask_b32_e32 v76, v132, v129, vcc
	s_lshl_b32 s9, s8, 3
	s_and_b32 s9, s9, 63
	v_readlane_b32 s11, v76, s9
	s_add_i32 s9, s9, 1
	s_lshl_b32 s11, s11, 10
	s_add_u32 s48, s72, s11
	s_addc_u32 s49, s73, 0
	global_load_dwordx4 v[112:115], v219, s[48:49]
	v_readlane_b32 s37, v76, s9
	s_add_i32 s9, s9, 1
	s_lshl_b32 s37, s37, 10
	s_add_u32 s50, s72, s37
	s_addc_u32 s51, s73, 0
	global_load_dwordx4 v[116:119], v219, s[50:51]
	v_readlane_b32 s11, v76, s9
	s_add_i32 s9, s9, 1
	s_lshl_b32 s11, s11, 10
	s_add_u32 s48, s72, s11
	s_addc_u32 s49, s73, 0
	global_load_dwordx4 v[120:123], v219, s[48:49]
	v_readlane_b32 s37, v76, s9
	s_add_i32 s9, s9, 1
	s_lshl_b32 s37, s37, 10
	s_add_u32 s50, s72, s37
	s_addc_u32 s51, s73, 0
	global_load_dwordx4 v[220:223], v219, s[50:51]
	v_readlane_b32 s11, v76, s9
	s_add_i32 s9, s9, 1
	s_lshl_b32 s11, s11, 10
	s_add_u32 s48, s72, s11
	s_addc_u32 s49, s73, 0
	global_load_dwordx4 v[224:227], v219, s[48:49]
	v_readlane_b32 s37, v76, s9
	s_add_i32 s9, s9, 1
	s_lshl_b32 s37, s37, 10
	s_add_u32 s50, s72, s37
	s_addc_u32 s51, s73, 0
	global_load_dwordx4 v[228:231], v219, s[50:51]
	v_readlane_b32 s11, v76, s9
	s_add_i32 s9, s9, 1
	s_lshl_b32 s11, s11, 10
	s_add_u32 s48, s72, s11
	s_addc_u32 s49, s73, 0
	global_load_dwordx4 v[232:235], v219, s[48:49]
	v_readlane_b32 s37, v76, s9
	s_lshl_b32 s37, s37, 10
	s_add_u32 s50, s72, s37
	s_addc_u32 s51, s73, 0
	global_load_dwordx4 v[236:239], v219, s[50:51]

; __device__ __forceinline__ float gelu_erf(float x) { return 0.5f * x * (1.f + erff(x * 0.70710678118654752f)); }
.Lpx_g2:
	s_andn2_saveexec_b64 s[4:5], s[4:5]
	v_mul_f32_e32 v76, v75, v75
	v_fmamk_f32 v77, v76, 0xba1345e1, v163
	v_fmaak_f32 v77, v76, v77, 0xbcdac9b8
	v_fmaak_f32 v77, v76, v77, 0x3de703be
	v_fmaak_f32 v77, v76, v77, 0xbec09330
	v_fmaak_f32 v76, v76, v77, 0x3e0375d0
	v_fma_f32 v76, |v75|, v76, |v75|
	s_or_b64 exec, exec, s[4:5]
	v_bfi_b32 v75, s2, v76, v75
	v_mul_f32_e32 v74, 0.5, v74
	v_add_f32_e32 v75, 1.0, v75
	v_mul_f32_e32 v74, v74, v75
	s_sub_i32 s9, s8, 3
	s_cmp_lt_u32 s9, 8
	s_cselect_b64 vcc, -1, 0
	v_cndmask_b32_e32 v76, v1, v133, vcc
	s_cmp_lt_u32 s8, 3
	s_cselect_b64 vcc, -1, 0
	s_cselect_b32 s9, s8, s9
	v_cndmask_b32_e32 v76, v76, v212, vcc
	v_mul_f32_e32 v74, v76, v74
	v_mul_f32_e32 v74, 0x3dba2e8c, v74
	s_lshl_b32 s9, s9, 3
	s_and_b32 s9, s9, 63
	v_readlane_b32 s70, v74, s9
	s_add_i32 s9, s9, 1
	v_readlane_b32 s68, v74, s9
	s_add_i32 s9, s9, 1
	v_readlane_b32 s66, v74, s9
	s_add_i32 s9, s9, 1
	v_readlane_b32 s64, v74, s9
	s_add_i32 s9, s9, 1
	v_readlane_b32 s36, v74, s9
	s_add_i32 s9, s9, 1
	v_readlane_b32 s14, v74, s9
	s_add_i32 s9, s9, 1
	v_readlane_b32 s10, v74, s9
	s_add_i32 s9, s9, 1
	v_readlane_b32 s4, v74, s9
	v_cvt_scalef32_pk_f32_fp4 v[40:41], v42, 1.0
	v_cvt_scalef32_pk_f32_fp4 v[44:45], v42, 1.0 op_sel:[1,0,0]
	v_cvt_scalef32_pk_f32_fp4 v[48:49], v42, 1.0 op_sel:[0,1,0]
	v_cvt_scalef32_pk_f32_fp4 v[52:53], v42, 1.0 op_sel:[1,1,0]
	v_cvt_scalef32_pk_f32_fp4 v[58:59], v43, 1.0
	v_cvt_scalef32_pk_f32_fp4 v[62:63], v43, 1.0 op_sel:[1,0,0]
	v_cvt_scalef32_pk_f32_fp4 v[66:67], v43, 1.0 op_sel:[0,1,0]
	v_cvt_scalef32_pk_f32_fp4 v[70:71], v43, 1.0 op_sel:[1,1,0]
	v_pk_fma_f32 v[158:159], v[40:41], s[70:71], v[158:159] op_sel_hi:[1,0,1]
	v_pk_fma_f32 v[160:161], v[44:45], s[70:71], v[160:161] op_sel_hi:[1,0,1]
	v_pk_fma_f32 v[240:241], v[48:49], s[70:71], v[240:241] op_sel_hi:[1,0,1]
	v_pk_fma_f32 v[242:243], v[52:53], s[70:71], v[242:243] op_sel_hi:[1,0,1]
	v_pk_fma_f32 v[244:245], v[58:59], s[70:71], v[244:245] op_sel_hi:[1,0,1]
	v_pk_fma_f32 v[246:247], v[62:63], s[70:71], v[246:247] op_sel_hi:[1,0,1]
	v_pk_fma_f32 v[248:249], v[66:67], s[70:71], v[248:249] op_sel_hi:[1,0,1]
	v_pk_fma_f32 v[124:125], v[70:71], s[70:71], v[124:125] op_sel_hi:[1,0,1]
	v_cvt_scalef32_pk_f32_fp4 v[40:41], v46, 1.0
	v_cvt_scalef32_pk_f32_fp4 v[44:45], v46, 1.0 op_sel:[1,0,0]
	v_cvt_scalef32_pk_f32_fp4 v[48:49], v46, 1.0 op_sel:[0,1,0]
	v_cvt_scalef32_pk_f32_fp4 v[52:53], v46, 1.0 op_sel:[1,1,0]
	v_cvt_scalef32_pk_f32_fp4 v[58:59], v47, 1.0
	v_cvt_scalef32_pk_f32_fp4 v[62:63], v47, 1.0 op_sel:[1,0,0]
	v_cvt_scalef32_pk_f32_fp4 v[66:67], v47, 1.0 op_sel:[0,1,0]
	v_cvt_scalef32_pk_f32_fp4 v[70:71], v47, 1.0 op_sel:[1,1,0]
	v_pk_fma_f32 v[158:159], v[40:41], s[68:69], v[158:159] op_sel_hi:[1,0,1]
	v_pk_fma_f32 v[160:161], v[44:45], s[68:69], v[160:161] op_sel_hi:[1,0,1]
	v_pk_fma_f32 v[240:241], v[48:49], s[68:69], v[240:241] op_sel_hi:[1,0,1]
	v_pk_fma_f32 v[242:243], v[52:53], s[68:69], v[242:243] op_sel_hi:[1,0,1]
	v_pk_fma_f32 v[244:245], v[58:59], s[68:69], v[244:245] op_sel_hi:[1,0,1]
	v_pk_fma_f32 v[246:247], v[62:63], s[68:69], v[246:247] op_sel_hi:[1,0,1]
	v_pk_fma_f32 v[248:249], v[66:67], s[68:69], v[248:249] op_sel_hi:[1,0,1]
	v_pk_fma_f32 v[124:125], v[70:71], s[68:69], v[124:125] op_sel_hi:[1,0,1]
	v_cvt_scalef32_pk_f32_fp4 v[40:41], v50, 1.0
	v_cvt_scalef32_pk_f32_fp4 v[44:45], v50, 1.0 op_sel:[1,0,0]
	v_cvt_scalef32_pk_f32_fp4 v[48:49], v50, 1.0 op_sel:[0,1,0]
	v_cvt_scalef32_pk_f32_fp4 v[52:53], v50, 1.0 op_sel:[1,1,0]
	v_cvt_scalef32_pk_f32_fp4 v[58:59], v51, 1.0
	v_cvt_scalef32_pk_f32_fp4 v[62:63], v51, 1.0 op_sel:[1,0,0]
	v_cvt_scalef32_pk_f32_fp4 v[66:67], v51, 1.0 op_sel:[0,1,0]
	v_cvt_scalef32_pk_f32_fp4 v[70:71], v51, 1.0 op_sel:[1,1,0]
	v_pk_fma_f32 v[158:159], v[40:41], s[66:67], v[158:159] op_sel_hi:[1,0,1]
	v_pk_fma_f32 v[160:161], v[44:45], s[66:67], v[160:161] op_sel_hi:[1,0,1]
	v_pk_fma_f32 v[240:241], v[48:49], s[66:67], v[240:241] op_sel_hi:[1,0,1]
	v_pk_fma_f32 v[242:243], v[52:53], s[66:67], v[242:243] op_sel_hi:[1,0,1]
	v_pk_fma_f32 v[244:245], v[58:59], s[66:67], v[244:245] op_sel_hi:[1,0,1]
	v_pk_fma_f32 v[246:247], v[62:63], s[66:67], v[246:247] op_sel_hi:[1,0,1]
	v_pk_fma_f32 v[248:249], v[66:67], s[66:67], v[248:249] op_sel_hi:[1,0,1]
	v_pk_fma_f32 v[124:125], v[70:71], s[66:67], v[124:125] op_sel_hi:[1,0,1]
	v_cvt_scalef32_pk_f32_fp4 v[40:41], v54, 1.0
	v_cvt_scalef32_pk_f32_fp4 v[44:45], v54, 1.0 op_sel:[1,0,0]
	v_cvt_scalef32_pk_f32_fp4 v[48:49], v54, 1.0 op_sel:[0,1,0]
	v_cvt_scalef32_pk_f32_fp4 v[52:53], v54, 1.0 op_sel:[1,1,0]
	v_cvt_scalef32_pk_f32_fp4 v[58:59], v55, 1.0
	v_cvt_scalef32_pk_f32_fp4 v[62:63], v55, 1.0 op_sel:[1,0,0]
	v_cvt_scalef32_pk_f32_fp4 v[66:67], v55, 1.0 op_sel:[0,1,0]
	v_cvt_scalef32_pk_f32_fp4 v[70:71], v55, 1.0 op_sel:[1,1,0]
	v_pk_fma_f32 v[158:159], v[40:41], s[64:65], v[158:159] op_sel_hi:[1,0,1]
	v_pk_fma_f32 v[160:161], v[44:45], s[64:65], v[160:161] op_sel_hi:[1,0,1]
	v_pk_fma_f32 v[240:241], v[48:49], s[64:65], v[240:241] op_sel_hi:[1,0,1]
	v_pk_fma_f32 v[242:243], v[52:53], s[64:65], v[242:243] op_sel_hi:[1,0,1]
	v_pk_fma_f32 v[244:245], v[58:59], s[64:65], v[244:245] op_sel_hi:[1,0,1]
	v_pk_fma_f32 v[246:247], v[62:63], s[64:65], v[246:247] op_sel_hi:[1,0,1]
	v_pk_fma_f32 v[248:249], v[66:67], s[64:65], v[248:249] op_sel_hi:[1,0,1]
	v_pk_fma_f32 v[124:125], v[70:71], s[64:65], v[124:125] op_sel_hi:[1,0,1]
	v_cvt_scalef32_pk_f32_fp4 v[40:41], v60, 1.0
	v_cvt_scalef32_pk_f32_fp4 v[44:45], v60, 1.0 op_sel:[1,0,0]
	v_cvt_scalef32_pk_f32_fp4 v[48:49], v60, 1.0 op_sel:[0,1,0]
; __device__ __forceinline__ void phase_expert(CArgs& A, int l, unsigned char* lds, int tid, bool dry = false) {
;     ...
;         PEER_LOAD(0, 0);
; #pragma unroll 1
;         for (int c2 = 0; c2 < 8; ++c2) {
;             PEER_LOAD(1, 2 * c2 + 1);
;             PEER_COMPUTE(0);
;             if (c2 < 7) PEER_LOAD(0, 2 * c2 + 2);
	v_cvt_scalef32_pk_f32_fp4 v[52:53], v60, 1.0 op_sel:[1,1,0]
	v_cvt_scalef32_pk_f32_fp4 v[58:59], v61, 1.0
	v_cvt_scalef32_pk_f32_fp4 v[62:63], v61, 1.0 op_sel:[1,0,0]
	v_cvt_scalef32_pk_f32_fp4 v[66:67], v61, 1.0 op_sel:[0,1,0]
	v_cvt_scalef32_pk_f32_fp4 v[70:71], v61, 1.0 op_sel:[1,1,0]
	v_pk_fma_f32 v[158:159], v[40:41], s[36:37], v[158:159] op_sel_hi:[1,0,1]
	v_pk_fma_f32 v[160:161], v[44:45], s[36:37], v[160:161] op_sel_hi:[1,0,1]
	v_pk_fma_f32 v[240:241], v[48:49], s[36:37], v[240:241] op_sel_hi:[1,0,1]
	v_pk_fma_f32 v[242:243], v[52:53], s[36:37], v[242:243] op_sel_hi:[1,0,1]
	v_pk_fma_f32 v[244:245], v[58:59], s[36:37], v[244:245] op_sel_hi:[1,0,1]
	v_pk_fma_f32 v[246:247], v[62:63], s[36:37], v[246:247] op_sel_hi:[1,0,1]
	v_pk_fma_f32 v[248:249], v[66:67], s[36:37], v[248:249] op_sel_hi:[1,0,1]
	v_pk_fma_f32 v[124:125], v[70:71], s[36:37], v[124:125] op_sel_hi:[1,0,1]
	v_cvt_scalef32_pk_f32_fp4 v[40:41], v64, 1.0
	v_cvt_scalef32_pk_f32_fp4 v[44:45], v64, 1.0 op_sel:[1,0,0]
	v_cvt_scalef32_pk_f32_fp4 v[48:49], v64, 1.0 op_sel:[0,1,0]
	v_cvt_scalef32_pk_f32_fp4 v[52:53], v64, 1.0 op_sel:[1,1,0]
	v_cvt_scalef32_pk_f32_fp4 v[58:59], v65, 1.0
	v_cvt_scalef32_pk_f32_fp4 v[62:63], v65, 1.0 op_sel:[1,0,0]
	v_cvt_scalef32_pk_f32_fp4 v[66:67], v65, 1.0 op_sel:[0,1,0]
	v_cvt_scalef32_pk_f32_fp4 v[70:71], v65, 1.0 op_sel:[1,1,0]
	v_pk_fma_f32 v[158:159], v[40:41], s[14:15], v[158:159] op_sel_hi:[1,0,1]
	v_pk_fma_f32 v[160:161], v[44:45], s[14:15], v[160:161] op_sel_hi:[1,0,1]
	v_pk_fma_f32 v[240:241], v[48:49], s[14:15], v[240:241] op_sel_hi:[1,0,1]
	v_pk_fma_f32 v[242:243], v[52:53], s[14:15], v[242:243] op_sel_hi:[1,0,1]
	v_pk_fma_f32 v[244:245], v[58:59], s[14:15], v[244:245] op_sel_hi:[1,0,1]
	v_pk_fma_f32 v[246:247], v[62:63], s[14:15], v[246:247] op_sel_hi:[1,0,1]
	v_pk_fma_f32 v[248:249], v[66:67], s[14:15], v[248:249] op_sel_hi:[1,0,1]
	v_pk_fma_f32 v[124:125], v[70:71], s[14:15], v[124:125] op_sel_hi:[1,0,1]
	v_cvt_scalef32_pk_f32_fp4 v[40:41], v68, 1.0
	v_cvt_scalef32_pk_f32_fp4 v[44:45], v68, 1.0 op_sel:[1,0,0]
	v_cvt_scalef32_pk_f32_fp4 v[48:49], v68, 1.0 op_sel:[0,1,0]
	v_cvt_scalef32_pk_f32_fp4 v[52:53], v68, 1.0 op_sel:[1,1,0]
	v_cvt_scalef32_pk_f32_fp4 v[58:59], v69, 1.0
	v_cvt_scalef32_pk_f32_fp4 v[62:63], v69, 1.0 op_sel:[1,0,0]
	v_cvt_scalef32_pk_f32_fp4 v[66:67], v69, 1.0 op_sel:[0,1,0]
	v_cvt_scalef32_pk_f32_fp4 v[70:71], v69, 1.0 op_sel:[1,1,0]
	v_pk_fma_f32 v[158:159], v[40:41], s[10:11], v[158:159] op_sel_hi:[1,0,1]
	v_pk_fma_f32 v[160:161], v[44:45], s[10:11], v[160:161] op_sel_hi:[1,0,1]
	v_pk_fma_f32 v[240:241], v[48:49], s[10:11], v[240:241] op_sel_hi:[1,0,1]
	v_pk_fma_f32 v[242:243], v[52:53], s[10:11], v[242:243] op_sel_hi:[1,0,1]
	v_pk_fma_f32 v[244:245], v[58:59], s[10:11], v[244:245] op_sel_hi:[1,0,1]
	v_pk_fma_f32 v[246:247], v[62:63], s[10:11], v[246:247] op_sel_hi:[1,0,1]
	v_pk_fma_f32 v[248:249], v[66:67], s[10:11], v[248:249] op_sel_hi:[1,0,1]
	v_pk_fma_f32 v[124:125], v[70:71], s[10:11], v[124:125] op_sel_hi:[1,0,1]
	v_cvt_scalef32_pk_f32_fp4 v[40:41], v72, 1.0
	v_cvt_scalef32_pk_f32_fp4 v[44:45], v72, 1.0 op_sel:[1,0,0]
	v_cvt_scalef32_pk_f32_fp4 v[48:49], v72, 1.0 op_sel:[0,1,0]
	v_cvt_scalef32_pk_f32_fp4 v[52:53], v72, 1.0 op_sel:[1,1,0]
	v_cvt_scalef32_pk_f32_fp4 v[58:59], v73, 1.0
	v_cvt_scalef32_pk_f32_fp4 v[62:63], v73, 1.0 op_sel:[1,0,0]
	v_cvt_scalef32_pk_f32_fp4 v[66:67], v73, 1.0 op_sel:[0,1,0]
	v_cvt_scalef32_pk_f32_fp4 v[70:71], v73, 1.0 op_sel:[1,1,0]
	v_pk_fma_f32 v[158:159], v[40:41], s[4:5], v[158:159] op_sel_hi:[1,0,1]
	v_pk_fma_f32 v[160:161], v[44:45], s[4:5], v[160:161] op_sel_hi:[1,0,1]
	v_pk_fma_f32 v[240:241], v[48:49], s[4:5], v[240:241] op_sel_hi:[1,0,1]
	v_pk_fma_f32 v[242:243], v[52:53], s[4:5], v[242:243] op_sel_hi:[1,0,1]
	v_pk_fma_f32 v[244:245], v[58:59], s[4:5], v[244:245] op_sel_hi:[1,0,1]
	v_pk_fma_f32 v[246:247], v[62:63], s[4:5], v[246:247] op_sel_hi:[1,0,1]
	v_pk_fma_f32 v[248:249], v[66:67], s[4:5], v[248:249] op_sel_hi:[1,0,1]
	v_pk_fma_f32 v[124:125], v[70:71], s[4:5], v[124:125] op_sel_hi:[1,0,1]
	s_add_i32 s0, s8, 3
	s_cmp_gt_u32 s0, 15
	s_cbranch_scc1 .Lpx_sk2
	s_cmp_lt_u32 s8, 8
	s_cselect_b64 vcc, -1, 0
	v_cndmask_b32_e32 v76, v132, v129, vcc
	s_lshl_b32 s9, s8, 3
	s_and_b32 s9, s9, 63
	v_readlane_b32 s11, v76, s9
	s_add_i32 s9, s9, 1
	s_lshl_b32 s11, s11, 10
	s_add_u32 s48, s72, s11
	s_addc_u32 s49, s73, 0
	global_load_dwordx4 v[40:43], v219, s[48:49]
	v_readlane_b32 s37, v76, s9
	s_add_i32 s9, s9, 1
	s_lshl_b32 s37, s37, 10
	s_add_u32 s50, s72, s37
	s_addc_u32 s51, s73, 0
	global_load_dwordx4 v[44:47], v219, s[50:51]
	v_readlane_b32 s11, v76, s9
	s_add_i32 s9, s9, 1
	s_lshl_b32 s11, s11, 10
	s_add_u32 s48, s72, s11
	s_addc_u32 s49, s73, 0
	global_load_dwordx4 v[48:51], v219, s[48:49]
	v_readlane_b32 s37, v76, s9
	s_add_i32 s9, s9, 1
	s_lshl_b32 s37, s37, 10
	s_add_u32 s50, s72, s37
	s_addc_u32 s51, s73, 0
	global_load_dwordx4 v[52:55], v219, s[50:51]
	v_readlane_b32 s11, v76, s9
	s_add_i32 s9, s9, 1
	s_lshl_b32 s11, s11, 10
	s_add_u32 s48, s72, s11
	s_addc_u32 s49, s73, 0
	global_load_dwordx4 v[58:61], v219, s[48:49]
	v_readlane_b32 s37, v76, s9
	s_add_i32 s9, s9, 1
	s_lshl_b32 s37, s37, 10
	s_add_u32 s50, s72, s37
	s_addc_u32 s51, s73, 0
	global_load_dwordx4 v[62:65], v219, s[50:51]
	v_readlane_b32 s11, v76, s9
	s_add_i32 s9, s9, 1
	s_lshl_b32 s11, s11, 10
	s_add_u32 s48, s72, s11
	s_addc_u32 s49, s73, 0
	global_load_dwordx4 v[66:69], v219, s[48:49]
	v_readlane_b32 s37, v76, s9
	s_lshl_b32 s37, s37, 10
	s_add_u32 s50, s72, s37
	s_addc_u32 s51, s73, 0
	global_load_dwordx4 v[70:73], v219, s[50:51]
